# stagger0 + S1 unused-MFMA removal + final-rmsnorm loop rewritten (4 rows x 2 buffers in flight, DPP row reduction, counted vmcnt)
# speedup vs baseline: 1.0074x; 1.0028x over previous
.LBB0_1366:
	s_cmp_lt_i32 s58, 8
	s_cselect_b64 s[0:1], -1, 0
	s_and_b64 s[0:1], s[0:1], s[72:73]
	s_andn2_b64 vcc, exec, s[0:1]
	s_cbranch_vccnz .LBB0_1372
	v_readlane_b32 s0, v252, 35
	v_readlane_b32 s1, v252, 26
	s_and_b32 s2, s95, -8
	s_lshl_b32 s3, s0, 13
	s_add_i32 s2, s2, s1
	s_add_i32 s4, s2, s3
	s_lshl_b32 s6, s4, 11
	s_add_u32 s10, s70, s6
	s_addc_u32 s11, s71, 0
	s_add_u32 s10, s10, 0x4000000
	s_addc_u32 s11, s11, 0
	s_lshl_b32 s6, s4, 6
	s_add_u32 s12, s70, s6
	s_addc_u32 s13, s71, 0
	s_add_u32 s12, s12, 0x400000
	s_addc_u32 s13, s13, 0
	s_lshl_b32 s6, s4, 12
	s_add_u32 s14, s68, s6
	s_addc_u32 s15, s69, 0
	v_lshlrev_b32_e32 v25, 5, v232
	global_load_dwordx4 v[0:3], v25, s[66:67] offset:16
	global_load_dwordx4 v[4:7], v25, s[66:67]
	global_load_dwordx4 v[8:11], v25, s[66:67] offset:2064
	global_load_dwordx4 v[12:15], v25, s[66:67] offset:2048
	v_lshlrev_b32_e32 v16, 4, v232
	v_add_u32_e32 v17, 0x80000, v16
	v_add_u32_e32 v18, 0x100000, v16
	v_add_u32_e32 v19, 0x180000, v16
	v_mov_b32_e32 v20, v25
	v_add_u32_e32 v21, 0x100000, v25
	v_add_u32_e32 v22, 0x200000, v25
	v_add_u32_e32 v23, 0x300000, v25
	v_lshrrev_b32_e32 v24, 4, v232
	v_and_b32_e32 v26, 15, v232
	v_lshlrev_b32_e32 v24, 14, v24
	v_lshl_or_b32 v24, v26, 2, v24
	v_mov_b32_e32 v28, 0x358637bd
	v_mov_b32_e32 v29, 0x260
	s_mov_b32 s5, 0xf800000
	global_load_dword v72, v24, s[12:13]
	global_load_dwordx4 v[40:43], v16, s[10:11]
	global_load_dwordx4 v[44:47], v16, s[10:11] offset:1024
	global_load_dwordx4 v[48:51], v17, s[10:11]
	global_load_dwordx4 v[52:55], v17, s[10:11] offset:1024
	global_load_dwordx4 v[56:59], v18, s[10:11]
	global_load_dwordx4 v[60:63], v18, s[10:11] offset:1024
	global_load_dwordx4 v[64:67], v19, s[10:11]
	global_load_dwordx4 v[68:71], v19, s[10:11] offset:1024
	s_add_u32 s10, s10, 0x200000
	s_addc_u32 s11, s11, 0
	s_add_u32 s12, s12, 0x10000
	s_addc_u32 s13, s13, 0
	global_load_dword v112, v24, s[12:13]
	global_load_dwordx4 v[80:83], v16, s[10:11]
	global_load_dwordx4 v[84:87], v16, s[10:11] offset:1024
	global_load_dwordx4 v[88:91], v17, s[10:11]
	global_load_dwordx4 v[92:95], v17, s[10:11] offset:1024
	global_load_dwordx4 v[96:99], v18, s[10:11]
	global_load_dwordx4 v[100:103], v18, s[10:11] offset:1024
	global_load_dwordx4 v[104:107], v19, s[10:11]
	global_load_dwordx4 v[108:111], v19, s[10:11] offset:1024
	s_waitcnt vmcnt(17)
	v_add_f32_dpp v26, v72, v72 quad_perm:[1,0,3,2] row_mask:0xf bank_mask:0xf
	s_nop 1
	v_add_f32_dpp v27, v26, v26 quad_perm:[2,3,0,1] row_mask:0xf bank_mask:0xf
	s_nop 1
	v_add_f32_dpp v26, v27, v27 row_half_mirror row_mask:0xf bank_mask:0xf
	s_nop 1
	v_add_f32_dpp v30, v26, v26 row_mirror row_mask:0xf bank_mask:0xf
	v_fmamk_f32 v30, v30, 0x3a800000, v28
	v_mul_f32_e32 v31, 0x4f800000, v30
	v_cmp_gt_f32_e32 vcc, s5, v30
	s_nop 1
	v_cndmask_b32_e32 v30, v30, v31, vcc
	v_sqrt_f32_e32 v31, v30
	s_nop 0
	v_add_u32_e32 v36, -1, v31
	v_add_u32_e32 v37, 1, v31
	v_fma_f32 v38, -v36, v31, v30
	v_fma_f32 v39, -v37, v31, v30
	v_cmp_ge_f32_e64 s[2:3], 0, v38
	s_nop 1
	v_cndmask_b32_e64 v31, v31, v36, s[2:3]
	v_cmp_lt_f32_e64 s[2:3], 0, v39
	s_nop 1
	v_cndmask_b32_e64 v31, v31, v37, s[2:3]
	v_mul_f32_e32 v36, 0x37800000, v31
	v_cndmask_b32_e32 v31, v31, v36, vcc
	v_cmp_class_f32_e32 vcc, v30, v29
	s_nop 1
	v_cndmask_b32_e32 v30, v31, v30, vcc
	v_div_scale_f32 v31, s[2:3], v30, v30, 1.0
	v_rcp_f32_e32 v36, v31
	v_div_scale_f32 v37, vcc, 1.0, v30, 1.0
	v_fma_f32 v38, -v31, v36, 1.0
	v_fmac_f32_e32 v36, v38, v36
	v_mul_f32_e32 v38, v37, v36
	v_fma_f32 v39, -v31, v38, v37
	v_fmac_f32_e32 v38, v39, v36
	v_fma_f32 v31, -v31, v38, v37
	v_div_fmas_f32 v31, v31, v36, v38
	v_div_fixup_f32 v38, v31, v30, 1.0
	s_nop 1
	v_readlane_b32 s20, v38, 0
	v_readlane_b32 s22, v38, 16
	v_readlane_b32 s24, v38, 32
	v_readlane_b32 s26, v38, 48
	s_waitcnt vmcnt(9)
	v_lshlrev_b32_e32 v120, 16, v40
	v_and_b32_e32 v121, 0xffff0000, v40
	v_lshlrev_b32_e32 v122, 16, v41
	v_and_b32_e32 v123, 0xffff0000, v41
	v_lshlrev_b32_e32 v124, 16, v42
	v_and_b32_e32 v125, 0xffff0000, v42
	v_lshlrev_b32_e32 v126, 16, v43
	v_and_b32_e32 v127, 0xffff0000, v43
	v_pk_mul_f32 v[120:121], s[20:21], v[120:121] op_sel_hi:[0,1]
	v_pk_mul_f32 v[122:123], s[20:21], v[122:123] op_sel_hi:[0,1]
	v_pk_mul_f32 v[124:125], s[20:21], v[124:125] op_sel_hi:[0,1]
	v_pk_mul_f32 v[126:127], s[20:21], v[126:127] op_sel_hi:[0,1]
	v_pk_mul_f32 v[120:121], v[4:5], v[120:121]
	v_pk_mul_f32 v[122:123], v[6:7], v[122:123]
	v_pk_mul_f32 v[124:125], v[0:1], v[124:125]
	v_pk_mul_f32 v[126:127], v[2:3], v[126:127]
	global_store_dwordx4 v20, v[120:123], s[14:15] nt
	global_store_dwordx4 v20, v[124:127], s[14:15] offset:16 nt
	v_lshlrev_b32_e32 v136, 16, v44
	v_and_b32_e32 v137, 0xffff0000, v44
	v_lshlrev_b32_e32 v138, 16, v45
	v_and_b32_e32 v139, 0xffff0000, v45
	v_lshlrev_b32_e32 v140, 16, v46
	v_and_b32_e32 v141, 0xffff0000, v46
	v_lshlrev_b32_e32 v142, 16, v47
	v_and_b32_e32 v143, 0xffff0000, v47
	v_pk_mul_f32 v[136:137], s[20:21], v[136:137] op_sel_hi:[0,1]
	v_pk_mul_f32 v[138:139], s[20:21], v[138:139] op_sel_hi:[0,1]
	v_pk_mul_f32 v[140:141], s[20:21], v[140:141] op_sel_hi:[0,1]
	v_pk_mul_f32 v[142:143], s[20:21], v[142:143] op_sel_hi:[0,1]
	v_pk_mul_f32 v[136:137], v[12:13], v[136:137]
	v_pk_mul_f32 v[138:139], v[14:15], v[138:139]
	v_pk_mul_f32 v[140:141], v[8:9], v[140:141]
	v_pk_mul_f32 v[142:143], v[10:11], v[142:143]
	global_store_dwordx4 v20, v[136:139], s[14:15] offset:2048 nt
	global_store_dwordx4 v20, v[140:143], s[14:15] offset:2064 nt
	v_lshlrev_b32_e32 v120, 16, v48
	v_and_b32_e32 v121, 0xffff0000, v48
	v_lshlrev_b32_e32 v122, 16, v49
	v_and_b32_e32 v123, 0xffff0000, v49
	v_lshlrev_b32_e32 v124, 16, v50
	v_and_b32_e32 v125, 0xffff0000, v50
	v_lshlrev_b32_e32 v126, 16, v51
	v_and_b32_e32 v127, 0xffff0000, v51
	v_pk_mul_f32 v[120:121], s[22:23], v[120:121] op_sel_hi:[0,1]
	v_pk_mul_f32 v[122:123], s[22:23], v[122:123] op_sel_hi:[0,1]
	v_pk_mul_f32 v[124:125], s[22:23], v[124:125] op_sel_hi:[0,1]
	v_pk_mul_f32 v[126:127], s[22:23], v[126:127] op_sel_hi:[0,1]
	v_pk_mul_f32 v[120:121], v[4:5], v[120:121]
	v_pk_mul_f32 v[122:123], v[6:7], v[122:123]
	v_pk_mul_f32 v[124:125], v[0:1], v[124:125]
	v_pk_mul_f32 v[126:127], v[2:3], v[126:127]
	global_store_dwordx4 v21, v[120:123], s[14:15] nt
	global_store_dwordx4 v21, v[124:127], s[14:15] offset:16 nt
	v_lshlrev_b32_e32 v136, 16, v52
	v_and_b32_e32 v137, 0xffff0000, v52
	v_lshlrev_b32_e32 v138, 16, v53
	v_and_b32_e32 v139, 0xffff0000, v53
	v_lshlrev_b32_e32 v140, 16, v54
	v_and_b32_e32 v141, 0xffff0000, v54
	v_lshlrev_b32_e32 v142, 16, v55
	v_and_b32_e32 v143, 0xffff0000, v55
	v_pk_mul_f32 v[136:137], s[22:23], v[136:137] op_sel_hi:[0,1]
	v_pk_mul_f32 v[138:139], s[22:23], v[138:139] op_sel_hi:[0,1]
	v_pk_mul_f32 v[140:141], s[22:23], v[140:141] op_sel_hi:[0,1]
	v_pk_mul_f32 v[142:143], s[22:23], v[142:143] op_sel_hi:[0,1]
	v_pk_mul_f32 v[136:137], v[12:13], v[136:137]
	v_pk_mul_f32 v[138:139], v[14:15], v[138:139]
	v_pk_mul_f32 v[140:141], v[8:9], v[140:141]
	v_pk_mul_f32 v[142:143], v[10:11], v[142:143]
	global_store_dwordx4 v21, v[136:139], s[14:15] offset:2048 nt
	global_store_dwordx4 v21, v[140:143], s[14:15] offset:2064 nt
	v_lshlrev_b32_e32 v120, 16, v56
	v_and_b32_e32 v121, 0xffff0000, v56
	v_lshlrev_b32_e32 v122, 16, v57
	v_and_b32_e32 v123, 0xffff0000, v57
	v_lshlrev_b32_e32 v124, 16, v58
	v_and_b32_e32 v125, 0xffff0000, v58
	v_lshlrev_b32_e32 v126, 16, v59
	v_and_b32_e32 v127, 0xffff0000, v59
	v_pk_mul_f32 v[120:121], s[24:25], v[120:121] op_sel_hi:[0,1]
	v_pk_mul_f32 v[122:123], s[24:25], v[122:123] op_sel_hi:[0,1]
	v_pk_mul_f32 v[124:125], s[24:25], v[124:125] op_sel_hi:[0,1]
	v_pk_mul_f32 v[126:127], s[24:25], v[126:127] op_sel_hi:[0,1]
	v_pk_mul_f32 v[120:121], v[4:5], v[120:121]
	v_pk_mul_f32 v[122:123], v[6:7], v[122:123]
	v_pk_mul_f32 v[124:125], v[0:1], v[124:125]
	v_pk_mul_f32 v[126:127], v[2:3], v[126:127]
	global_store_dwordx4 v22, v[120:123], s[14:15] nt
	global_store_dwordx4 v22, v[124:127], s[14:15] offset:16 nt
	v_lshlrev_b32_e32 v136, 16, v60
	v_and_b32_e32 v137, 0xffff0000, v60
	v_lshlrev_b32_e32 v138, 16, v61
	v_and_b32_e32 v139, 0xffff0000, v61
	v_lshlrev_b32_e32 v140, 16, v62
	v_and_b32_e32 v141, 0xffff0000, v62
	v_lshlrev_b32_e32 v142, 16, v63
	v_and_b32_e32 v143, 0xffff0000, v63
	v_pk_mul_f32 v[136:137], s[24:25], v[136:137] op_sel_hi:[0,1]
	v_pk_mul_f32 v[138:139], s[24:25], v[138:139] op_sel_hi:[0,1]
	v_pk_mul_f32 v[140:141], s[24:25], v[140:141] op_sel_hi:[0,1]
	v_pk_mul_f32 v[142:143], s[24:25], v[142:143] op_sel_hi:[0,1]
	v_pk_mul_f32 v[136:137], v[12:13], v[136:137]
	v_pk_mul_f32 v[138:139], v[14:15], v[138:139]
	v_pk_mul_f32 v[140:141], v[8:9], v[140:141]
	v_pk_mul_f32 v[142:143], v[10:11], v[142:143]
	global_store_dwordx4 v22, v[136:139], s[14:15] offset:2048 nt
	global_store_dwordx4 v22, v[140:143], s[14:15] offset:2064 nt
	v_lshlrev_b32_e32 v120, 16, v64
	v_and_b32_e32 v121, 0xffff0000, v64
	v_lshlrev_b32_e32 v122, 16, v65
	v_and_b32_e32 v123, 0xffff0000, v65
	v_lshlrev_b32_e32 v124, 16, v66
	v_and_b32_e32 v125, 0xffff0000, v66
	v_lshlrev_b32_e32 v126, 16, v67
	v_and_b32_e32 v127, 0xffff0000, v67
	v_pk_mul_f32 v[120:121], s[26:27], v[120:121] op_sel_hi:[0,1]
	v_pk_mul_f32 v[122:123], s[26:27], v[122:123] op_sel_hi:[0,1]
	v_pk_mul_f32 v[124:125], s[26:27], v[124:125] op_sel_hi:[0,1]
	v_pk_mul_f32 v[126:127], s[26:27], v[126:127] op_sel_hi:[0,1]
	v_pk_mul_f32 v[120:121], v[4:5], v[120:121]
	v_pk_mul_f32 v[122:123], v[6:7], v[122:123]
	v_pk_mul_f32 v[124:125], v[0:1], v[124:125]
	v_pk_mul_f32 v[126:127], v[2:3], v[126:127]
	global_store_dwordx4 v23, v[120:123], s[14:15] nt
	global_store_dwordx4 v23, v[124:127], s[14:15] offset:16 nt
	v_lshlrev_b32_e32 v136, 16, v68
	v_and_b32_e32 v137, 0xffff0000, v68
	v_lshlrev_b32_e32 v138, 16, v69
	v_and_b32_e32 v139, 0xffff0000, v69
	v_lshlrev_b32_e32 v140, 16, v70
	v_and_b32_e32 v141, 0xffff0000, v70
	v_lshlrev_b32_e32 v142, 16, v71
	v_and_b32_e32 v143, 0xffff0000, v71
	v_pk_mul_f32 v[136:137], s[26:27], v[136:137] op_sel_hi:[0,1]
	v_pk_mul_f32 v[138:139], s[26:27], v[138:139] op_sel_hi:[0,1]
	v_pk_mul_f32 v[140:141], s[26:27], v[140:141] op_sel_hi:[0,1]
	v_pk_mul_f32 v[142:143], s[26:27], v[142:143] op_sel_hi:[0,1]
	v_pk_mul_f32 v[136:137], v[12:13], v[136:137]
	v_pk_mul_f32 v[138:139], v[14:15], v[138:139]
	v_pk_mul_f32 v[140:141], v[8:9], v[140:141]
	v_pk_mul_f32 v[142:143], v[10:11], v[142:143]
	global_store_dwordx4 v23, v[136:139], s[14:15] offset:2048 nt
	global_store_dwordx4 v23, v[140:143], s[14:15] offset:2064 nt
	s_add_u32 s14, s14, 0x400000
	s_addc_u32 s15, s15, 0
	s_add_u32 s10, s10, 0x200000
	s_addc_u32 s11, s11, 0
	s_add_u32 s12, s12, 0x10000
	s_addc_u32 s13, s13, 0
	global_load_dword v72, v24, s[12:13]
	global_load_dwordx4 v[40:43], v16, s[10:11]
	global_load_dwordx4 v[44:47], v16, s[10:11] offset:1024
	global_load_dwordx4 v[48:51], v17, s[10:11]
	global_load_dwordx4 v[52:55], v17, s[10:11] offset:1024
	global_load_dwordx4 v[56:59], v18, s[10:11]
	global_load_dwordx4 v[60:63], v18, s[10:11] offset:1024
	global_load_dwordx4 v[64:67], v19, s[10:11]
	global_load_dwordx4 v[68:71], v19, s[10:11] offset:1024
	s_waitcnt vmcnt(33)
	v_add_f32_dpp v26, v112, v112 quad_perm:[1,0,3,2] row_mask:0xf bank_mask:0xf
	s_nop 1
	v_add_f32_dpp v27, v26, v26 quad_perm:[2,3,0,1] row_mask:0xf bank_mask:0xf
	s_nop 1
	v_add_f32_dpp v26, v27, v27 row_half_mirror row_mask:0xf bank_mask:0xf
	s_nop 1
	v_add_f32_dpp v30, v26, v26 row_mirror row_mask:0xf bank_mask:0xf
	v_fmamk_f32 v30, v30, 0x3a800000, v28
	v_mul_f32_e32 v31, 0x4f800000, v30
	v_cmp_gt_f32_e32 vcc, s5, v30
	s_nop 1
	v_cndmask_b32_e32 v30, v30, v31, vcc
	v_sqrt_f32_e32 v31, v30
	s_nop 0
	v_add_u32_e32 v36, -1, v31
	v_add_u32_e32 v37, 1, v31
	v_fma_f32 v38, -v36, v31, v30
	v_fma_f32 v39, -v37, v31, v30
	v_cmp_ge_f32_e64 s[2:3], 0, v38
	s_nop 1
	v_cndmask_b32_e64 v31, v31, v36, s[2:3]
	v_cmp_lt_f32_e64 s[2:3], 0, v39
	s_nop 1
	v_cndmask_b32_e64 v31, v31, v37, s[2:3]
	v_mul_f32_e32 v36, 0x37800000, v31
	v_cndmask_b32_e32 v31, v31, v36, vcc
	v_cmp_class_f32_e32 vcc, v30, v29
	s_nop 1
	v_cndmask_b32_e32 v30, v31, v30, vcc
	v_div_scale_f32 v31, s[2:3], v30, v30, 1.0
	v_rcp_f32_e32 v36, v31
	v_div_scale_f32 v37, vcc, 1.0, v30, 1.0
	v_fma_f32 v38, -v31, v36, 1.0
	v_fmac_f32_e32 v36, v38, v36
	v_mul_f32_e32 v38, v37, v36
	v_fma_f32 v39, -v31, v38, v37
	v_fmac_f32_e32 v38, v39, v36
	v_fma_f32 v31, -v31, v38, v37
	v_div_fmas_f32 v31, v31, v36, v38
	v_div_fixup_f32 v38, v31, v30, 1.0
	s_nop 1
	v_readlane_b32 s20, v38, 0
	v_readlane_b32 s22, v38, 16
	v_readlane_b32 s24, v38, 32
	v_readlane_b32 s26, v38, 48
	s_waitcnt vmcnt(25)
	v_lshlrev_b32_e32 v120, 16, v80
	v_and_b32_e32 v121, 0xffff0000, v80
	v_lshlrev_b32_e32 v122, 16, v81
	v_and_b32_e32 v123, 0xffff0000, v81
	v_lshlrev_b32_e32 v124, 16, v82
	v_and_b32_e32 v125, 0xffff0000, v82
	v_lshlrev_b32_e32 v126, 16, v83
	v_and_b32_e32 v127, 0xffff0000, v83
	v_pk_mul_f32 v[120:121], s[20:21], v[120:121] op_sel_hi:[0,1]
	v_pk_mul_f32 v[122:123], s[20:21], v[122:123] op_sel_hi:[0,1]
	v_pk_mul_f32 v[124:125], s[20:21], v[124:125] op_sel_hi:[0,1]
	v_pk_mul_f32 v[126:127], s[20:21], v[126:127] op_sel_hi:[0,1]
	v_pk_mul_f32 v[120:121], v[4:5], v[120:121]
	v_pk_mul_f32 v[122:123], v[6:7], v[122:123]
	v_pk_mul_f32 v[124:125], v[0:1], v[124:125]
	v_pk_mul_f32 v[126:127], v[2:3], v[126:127]
	global_store_dwordx4 v20, v[120:123], s[14:15] nt
	global_store_dwordx4 v20, v[124:127], s[14:15] offset:16 nt
	v_lshlrev_b32_e32 v136, 16, v84
	v_and_b32_e32 v137, 0xffff0000, v84
	v_lshlrev_b32_e32 v138, 16, v85
	v_and_b32_e32 v139, 0xffff0000, v85
	v_lshlrev_b32_e32 v140, 16, v86
	v_and_b32_e32 v141, 0xffff0000, v86
	v_lshlrev_b32_e32 v142, 16, v87
	v_and_b32_e32 v143, 0xffff0000, v87
	v_pk_mul_f32 v[136:137], s[20:21], v[136:137] op_sel_hi:[0,1]
	v_pk_mul_f32 v[138:139], s[20:21], v[138:139] op_sel_hi:[0,1]
	v_pk_mul_f32 v[140:141], s[20:21], v[140:141] op_sel_hi:[0,1]
	v_pk_mul_f32 v[142:143], s[20:21], v[142:143] op_sel_hi:[0,1]
	v_pk_mul_f32 v[136:137], v[12:13], v[136:137]
	v_pk_mul_f32 v[138:139], v[14:15], v[138:139]
	v_pk_mul_f32 v[140:141], v[8:9], v[140:141]
	v_pk_mul_f32 v[142:143], v[10:11], v[142:143]
	global_store_dwordx4 v20, v[136:139], s[14:15] offset:2048 nt
	global_store_dwordx4 v20, v[140:143], s[14:15] offset:2064 nt
	v_lshlrev_b32_e32 v120, 16, v88
	v_and_b32_e32 v121, 0xffff0000, v88
	v_lshlrev_b32_e32 v122, 16, v89
	v_and_b32_e32 v123, 0xffff0000, v89
	v_lshlrev_b32_e32 v124, 16, v90
	v_and_b32_e32 v125, 0xffff0000, v90
	v_lshlrev_b32_e32 v126, 16, v91
	v_and_b32_e32 v127, 0xffff0000, v91
	v_pk_mul_f32 v[120:121], s[22:23], v[120:121] op_sel_hi:[0,1]
	v_pk_mul_f32 v[122:123], s[22:23], v[122:123] op_sel_hi:[0,1]
	v_pk_mul_f32 v[124:125], s[22:23], v[124:125] op_sel_hi:[0,1]
	v_pk_mul_f32 v[126:127], s[22:23], v[126:127] op_sel_hi:[0,1]
	v_pk_mul_f32 v[120:121], v[4:5], v[120:121]
	v_pk_mul_f32 v[122:123], v[6:7], v[122:123]
	v_pk_mul_f32 v[124:125], v[0:1], v[124:125]
	v_pk_mul_f32 v[126:127], v[2:3], v[126:127]
	global_store_dwordx4 v21, v[120:123], s[14:15] nt
	global_store_dwordx4 v21, v[124:127], s[14:15] offset:16 nt
	v_lshlrev_b32_e32 v136, 16, v92
	v_and_b32_e32 v137, 0xffff0000, v92
	v_lshlrev_b32_e32 v138, 16, v93
	v_and_b32_e32 v139, 0xffff0000, v93
	v_lshlrev_b32_e32 v140, 16, v94
	v_and_b32_e32 v141, 0xffff0000, v94
	v_lshlrev_b32_e32 v142, 16, v95
	v_and_b32_e32 v143, 0xffff0000, v95
	v_pk_mul_f32 v[136:137], s[22:23], v[136:137] op_sel_hi:[0,1]
	v_pk_mul_f32 v[138:139], s[22:23], v[138:139] op_sel_hi:[0,1]
	v_pk_mul_f32 v[140:141], s[22:23], v[140:141] op_sel_hi:[0,1]
	v_pk_mul_f32 v[142:143], s[22:23], v[142:143] op_sel_hi:[0,1]
	v_pk_mul_f32 v[136:137], v[12:13], v[136:137]
	v_pk_mul_f32 v[138:139], v[14:15], v[138:139]
	v_pk_mul_f32 v[140:141], v[8:9], v[140:141]
	v_pk_mul_f32 v[142:143], v[10:11], v[142:143]
	global_store_dwordx4 v21, v[136:139], s[14:15] offset:2048 nt
	global_store_dwordx4 v21, v[140:143], s[14:15] offset:2064 nt
	v_lshlrev_b32_e32 v120, 16, v96
	v_and_b32_e32 v121, 0xffff0000, v96
	v_lshlrev_b32_e32 v122, 16, v97
	v_and_b32_e32 v123, 0xffff0000, v97
	v_lshlrev_b32_e32 v124, 16, v98
	v_and_b32_e32 v125, 0xffff0000, v98
	v_lshlrev_b32_e32 v126, 16, v99
	v_and_b32_e32 v127, 0xffff0000, v99
	v_pk_mul_f32 v[120:121], s[24:25], v[120:121] op_sel_hi:[0,1]
	v_pk_mul_f32 v[122:123], s[24:25], v[122:123] op_sel_hi:[0,1]
	v_pk_mul_f32 v[124:125], s[24:25], v[124:125] op_sel_hi:[0,1]
	v_pk_mul_f32 v[126:127], s[24:25], v[126:127] op_sel_hi:[0,1]
	v_pk_mul_f32 v[120:121], v[4:5], v[120:121]
	v_pk_mul_f32 v[122:123], v[6:7], v[122:123]
	v_pk_mul_f32 v[124:125], v[0:1], v[124:125]
	v_pk_mul_f32 v[126:127], v[2:3], v[126:127]
	global_store_dwordx4 v22, v[120:123], s[14:15] nt
	global_store_dwordx4 v22, v[124:127], s[14:15] offset:16 nt
	v_lshlrev_b32_e32 v136, 16, v100
	v_and_b32_e32 v137, 0xffff0000, v100
	v_lshlrev_b32_e32 v138, 16, v101
	v_and_b32_e32 v139, 0xffff0000, v101
	v_lshlrev_b32_e32 v140, 16, v102
	v_and_b32_e32 v141, 0xffff0000, v102
	v_lshlrev_b32_e32 v142, 16, v103
	v_and_b32_e32 v143, 0xffff0000, v103
	v_pk_mul_f32 v[136:137], s[24:25], v[136:137] op_sel_hi:[0,1]
	v_pk_mul_f32 v[138:139], s[24:25], v[138:139] op_sel_hi:[0,1]
	v_pk_mul_f32 v[140:141], s[24:25], v[140:141] op_sel_hi:[0,1]
	v_pk_mul_f32 v[142:143], s[24:25], v[142:143] op_sel_hi:[0,1]
	v_pk_mul_f32 v[136:137], v[12:13], v[136:137]
	v_pk_mul_f32 v[138:139], v[14:15], v[138:139]
	v_pk_mul_f32 v[140:141], v[8:9], v[140:141]
	v_pk_mul_f32 v[142:143], v[10:11], v[142:143]
	global_store_dwordx4 v22, v[136:139], s[14:15] offset:2048 nt
	global_store_dwordx4 v22, v[140:143], s[14:15] offset:2064 nt
	v_lshlrev_b32_e32 v120, 16, v104
	v_and_b32_e32 v121, 0xffff0000, v104
	v_lshlrev_b32_e32 v122, 16, v105
	v_and_b32_e32 v123, 0xffff0000, v105
	v_lshlrev_b32_e32 v124, 16, v106
	v_and_b32_e32 v125, 0xffff0000, v106
	v_lshlrev_b32_e32 v126, 16, v107
	v_and_b32_e32 v127, 0xffff0000, v107
	v_pk_mul_f32 v[120:121], s[26:27], v[120:121] op_sel_hi:[0,1]
	v_pk_mul_f32 v[122:123], s[26:27], v[122:123] op_sel_hi:[0,1]
	v_pk_mul_f32 v[124:125], s[26:27], v[124:125] op_sel_hi:[0,1]
	v_pk_mul_f32 v[126:127], s[26:27], v[126:127] op_sel_hi:[0,1]
	v_pk_mul_f32 v[120:121], v[4:5], v[120:121]
	v_pk_mul_f32 v[122:123], v[6:7], v[122:123]
	v_pk_mul_f32 v[124:125], v[0:1], v[124:125]
	v_pk_mul_f32 v[126:127], v[2:3], v[126:127]
	global_store_dwordx4 v23, v[120:123], s[14:15] nt
	global_store_dwordx4 v23, v[124:127], s[14:15] offset:16 nt
	v_lshlrev_b32_e32 v136, 16, v108
	v_and_b32_e32 v137, 0xffff0000, v108
	v_lshlrev_b32_e32 v138, 16, v109
	v_and_b32_e32 v139, 0xffff0000, v109
	v_lshlrev_b32_e32 v140, 16, v110
	v_and_b32_e32 v141, 0xffff0000, v110
	v_lshlrev_b32_e32 v142, 16, v111
	v_and_b32_e32 v143, 0xffff0000, v111
	v_pk_mul_f32 v[136:137], s[26:27], v[136:137] op_sel_hi:[0,1]
	v_pk_mul_f32 v[138:139], s[26:27], v[138:139] op_sel_hi:[0,1]
	v_pk_mul_f32 v[140:141], s[26:27], v[140:141] op_sel_hi:[0,1]
	v_pk_mul_f32 v[142:143], s[26:27], v[142:143] op_sel_hi:[0,1]
	v_pk_mul_f32 v[136:137], v[12:13], v[136:137]
	v_pk_mul_f32 v[138:139], v[14:15], v[138:139]
	v_pk_mul_f32 v[140:141], v[8:9], v[140:141]
	v_pk_mul_f32 v[142:143], v[10:11], v[142:143]
	global_store_dwordx4 v23, v[136:139], s[14:15] offset:2048 nt
	global_store_dwordx4 v23, v[140:143], s[14:15] offset:2064 nt
	s_add_u32 s14, s14, 0x400000
	s_addc_u32 s15, s15, 0
	s_add_u32 s10, s10, 0x200000
	s_addc_u32 s11, s11, 0
	s_add_u32 s12, s12, 0x10000
	s_addc_u32 s13, s13, 0
	global_load_dword v112, v24, s[12:13]
	global_load_dwordx4 v[80:83], v16, s[10:11]
	global_load_dwordx4 v[84:87], v16, s[10:11] offset:1024
	global_load_dwordx4 v[88:91], v17, s[10:11]
	global_load_dwordx4 v[92:95], v17, s[10:11] offset:1024
	global_load_dwordx4 v[96:99], v18, s[10:11]
	global_load_dwordx4 v[100:103], v18, s[10:11] offset:1024
	global_load_dwordx4 v[104:107], v19, s[10:11]
	global_load_dwordx4 v[108:111], v19, s[10:11] offset:1024
	s_waitcnt vmcnt(33)
	v_add_f32_dpp v26, v72, v72 quad_perm:[1,0,3,2] row_mask:0xf bank_mask:0xf
	s_nop 1
	v_add_f32_dpp v27, v26, v26 quad_perm:[2,3,0,1] row_mask:0xf bank_mask:0xf
	s_nop 1
	v_add_f32_dpp v26, v27, v27 row_half_mirror row_mask:0xf bank_mask:0xf
	s_nop 1
	v_add_f32_dpp v30, v26, v26 row_mirror row_mask:0xf bank_mask:0xf
	v_fmamk_f32 v30, v30, 0x3a800000, v28
	v_mul_f32_e32 v31, 0x4f800000, v30
	v_cmp_gt_f32_e32 vcc, s5, v30
	s_nop 1
	v_cndmask_b32_e32 v30, v30, v31, vcc
	v_sqrt_f32_e32 v31, v30
	s_nop 0
	v_add_u32_e32 v36, -1, v31
	v_add_u32_e32 v37, 1, v31
	v_fma_f32 v38, -v36, v31, v30
	v_fma_f32 v39, -v37, v31, v30
	v_cmp_ge_f32_e64 s[2:3], 0, v38
	s_nop 1
	v_cndmask_b32_e64 v31, v31, v36, s[2:3]
	v_cmp_lt_f32_e64 s[2:3], 0, v39
	s_nop 1
	v_cndmask_b32_e64 v31, v31, v37, s[2:3]
	v_mul_f32_e32 v36, 0x37800000, v31
	v_cndmask_b32_e32 v31, v31, v36, vcc
	v_cmp_class_f32_e32 vcc, v30, v29
	s_nop 1
	v_cndmask_b32_e32 v30, v31, v30, vcc
	v_div_scale_f32 v31, s[2:3], v30, v30, 1.0
	v_rcp_f32_e32 v36, v31
	v_div_scale_f32 v37, vcc, 1.0, v30, 1.0
	v_fma_f32 v38, -v31, v36, 1.0
	v_fmac_f32_e32 v36, v38, v36
	v_mul_f32_e32 v38, v37, v36
	v_fma_f32 v39, -v31, v38, v37
	v_fmac_f32_e32 v38, v39, v36
	v_fma_f32 v31, -v31, v38, v37
	v_div_fmas_f32 v31, v31, v36, v38
	v_div_fixup_f32 v38, v31, v30, 1.0
	s_nop 1
	v_readlane_b32 s20, v38, 0
	v_readlane_b32 s22, v38, 16
	v_readlane_b32 s24, v38, 32
	v_readlane_b32 s26, v38, 48
	s_waitcnt vmcnt(25)
	v_lshlrev_b32_e32 v120, 16, v40
	v_and_b32_e32 v121, 0xffff0000, v40
	v_lshlrev_b32_e32 v122, 16, v41
	v_and_b32_e32 v123, 0xffff0000, v41
	v_lshlrev_b32_e32 v124, 16, v42
	v_and_b32_e32 v125, 0xffff0000, v42
	v_lshlrev_b32_e32 v126, 16, v43
	v_and_b32_e32 v127, 0xffff0000, v43
	v_pk_mul_f32 v[120:121], s[20:21], v[120:121] op_sel_hi:[0,1]
	v_pk_mul_f32 v[122:123], s[20:21], v[122:123] op_sel_hi:[0,1]
	v_pk_mul_f32 v[124:125], s[20:21], v[124:125] op_sel_hi:[0,1]
	v_pk_mul_f32 v[126:127], s[20:21], v[126:127] op_sel_hi:[0,1]
	v_pk_mul_f32 v[120:121], v[4:5], v[120:121]
	v_pk_mul_f32 v[122:123], v[6:7], v[122:123]
	v_pk_mul_f32 v[124:125], v[0:1], v[124:125]
	v_pk_mul_f32 v[126:127], v[2:3], v[126:127]
	global_store_dwordx4 v20, v[120:123], s[14:15] nt
	global_store_dwordx4 v20, v[124:127], s[14:15] offset:16 nt
	v_lshlrev_b32_e32 v136, 16, v44
	v_and_b32_e32 v137, 0xffff0000, v44
	v_lshlrev_b32_e32 v138, 16, v45
	v_and_b32_e32 v139, 0xffff0000, v45
	v_lshlrev_b32_e32 v140, 16, v46
	v_and_b32_e32 v141, 0xffff0000, v46
	v_lshlrev_b32_e32 v142, 16, v47
	v_and_b32_e32 v143, 0xffff0000, v47
	v_pk_mul_f32 v[136:137], s[20:21], v[136:137] op_sel_hi:[0,1]
	v_pk_mul_f32 v[138:139], s[20:21], v[138:139] op_sel_hi:[0,1]
	v_pk_mul_f32 v[140:141], s[20:21], v[140:141] op_sel_hi:[0,1]
	v_pk_mul_f32 v[142:143], s[20:21], v[142:143] op_sel_hi:[0,1]
	v_pk_mul_f32 v[136:137], v[12:13], v[136:137]
	v_pk_mul_f32 v[138:139], v[14:15], v[138:139]
	v_pk_mul_f32 v[140:141], v[8:9], v[140:141]
	v_pk_mul_f32 v[142:143], v[10:11], v[142:143]
	global_store_dwordx4 v20, v[136:139], s[14:15] offset:2048 nt
	global_store_dwordx4 v20, v[140:143], s[14:15] offset:2064 nt
	v_lshlrev_b32_e32 v120, 16, v48
	v_and_b32_e32 v121, 0xffff0000, v48
	v_lshlrev_b32_e32 v122, 16, v49
	v_and_b32_e32 v123, 0xffff0000, v49
	v_lshlrev_b32_e32 v124, 16, v50
	v_and_b32_e32 v125, 0xffff0000, v50
	v_lshlrev_b32_e32 v126, 16, v51
	v_and_b32_e32 v127, 0xffff0000, v51
	v_pk_mul_f32 v[120:121], s[22:23], v[120:121] op_sel_hi:[0,1]
	v_pk_mul_f32 v[122:123], s[22:23], v[122:123] op_sel_hi:[0,1]
	v_pk_mul_f32 v[124:125], s[22:23], v[124:125] op_sel_hi:[0,1]
	v_pk_mul_f32 v[126:127], s[22:23], v[126:127] op_sel_hi:[0,1]
	v_pk_mul_f32 v[120:121], v[4:5], v[120:121]
	v_pk_mul_f32 v[122:123], v[6:7], v[122:123]
	v_pk_mul_f32 v[124:125], v[0:1], v[124:125]
	v_pk_mul_f32 v[126:127], v[2:3], v[126:127]
	global_store_dwordx4 v21, v[120:123], s[14:15] nt
	global_store_dwordx4 v21, v[124:127], s[14:15] offset:16 nt
	v_lshlrev_b32_e32 v136, 16, v52
	v_and_b32_e32 v137, 0xffff0000, v52
	v_lshlrev_b32_e32 v138, 16, v53
	v_and_b32_e32 v139, 0xffff0000, v53
	v_lshlrev_b32_e32 v140, 16, v54
	v_and_b32_e32 v141, 0xffff0000, v54
	v_lshlrev_b32_e32 v142, 16, v55
	v_and_b32_e32 v143, 0xffff0000, v55
	v_pk_mul_f32 v[136:137], s[22:23], v[136:137] op_sel_hi:[0,1]
	v_pk_mul_f32 v[138:139], s[22:23], v[138:139] op_sel_hi:[0,1]
	v_pk_mul_f32 v[140:141], s[22:23], v[140:141] op_sel_hi:[0,1]
	v_pk_mul_f32 v[142:143], s[22:23], v[142:143] op_sel_hi:[0,1]
	v_pk_mul_f32 v[136:137], v[12:13], v[136:137]
	v_pk_mul_f32 v[138:139], v[14:15], v[138:139]
	v_pk_mul_f32 v[140:141], v[8:9], v[140:141]
	v_pk_mul_f32 v[142:143], v[10:11], v[142:143]
	global_store_dwordx4 v21, v[136:139], s[14:15] offset:2048 nt
	global_store_dwordx4 v21, v[140:143], s[14:15] offset:2064 nt
	v_lshlrev_b32_e32 v120, 16, v56
	v_and_b32_e32 v121, 0xffff0000, v56
	v_lshlrev_b32_e32 v122, 16, v57
	v_and_b32_e32 v123, 0xffff0000, v57
	v_lshlrev_b32_e32 v124, 16, v58
	v_and_b32_e32 v125, 0xffff0000, v58
	v_lshlrev_b32_e32 v126, 16, v59
	v_and_b32_e32 v127, 0xffff0000, v59
	v_pk_mul_f32 v[120:121], s[24:25], v[120:121] op_sel_hi:[0,1]
	v_pk_mul_f32 v[122:123], s[24:25], v[122:123] op_sel_hi:[0,1]
	v_pk_mul_f32 v[124:125], s[24:25], v[124:125] op_sel_hi:[0,1]
	v_pk_mul_f32 v[126:127], s[24:25], v[126:127] op_sel_hi:[0,1]
	v_pk_mul_f32 v[120:121], v[4:5], v[120:121]
	v_pk_mul_f32 v[122:123], v[6:7], v[122:123]
	v_pk_mul_f32 v[124:125], v[0:1], v[124:125]
	v_pk_mul_f32 v[126:127], v[2:3], v[126:127]
	global_store_dwordx4 v22, v[120:123], s[14:15] nt
	global_store_dwordx4 v22, v[124:127], s[14:15] offset:16 nt
	v_lshlrev_b32_e32 v136, 16, v60
	v_and_b32_e32 v137, 0xffff0000, v60
	v_lshlrev_b32_e32 v138, 16, v61
	v_and_b32_e32 v139, 0xffff0000, v61
	v_lshlrev_b32_e32 v140, 16, v62
	v_and_b32_e32 v141, 0xffff0000, v62
	v_lshlrev_b32_e32 v142, 16, v63
	v_and_b32_e32 v143, 0xffff0000, v63
	v_pk_mul_f32 v[136:137], s[24:25], v[136:137] op_sel_hi:[0,1]
	v_pk_mul_f32 v[138:139], s[24:25], v[138:139] op_sel_hi:[0,1]
	v_pk_mul_f32 v[140:141], s[24:25], v[140:141] op_sel_hi:[0,1]
	v_pk_mul_f32 v[142:143], s[24:25], v[142:143] op_sel_hi:[0,1]
	v_pk_mul_f32 v[136:137], v[12:13], v[136:137]
	v_pk_mul_f32 v[138:139], v[14:15], v[138:139]
	v_pk_mul_f32 v[140:141], v[8:9], v[140:141]
	v_pk_mul_f32 v[142:143], v[10:11], v[142:143]
	global_store_dwordx4 v22, v[136:139], s[14:15] offset:2048 nt
	global_store_dwordx4 v22, v[140:143], s[14:15] offset:2064 nt
	v_lshlrev_b32_e32 v120, 16, v64
	v_and_b32_e32 v121, 0xffff0000, v64
	v_lshlrev_b32_e32 v122, 16, v65
	v_and_b32_e32 v123, 0xffff0000, v65
	v_lshlrev_b32_e32 v124, 16, v66
	v_and_b32_e32 v125, 0xffff0000, v66
	v_lshlrev_b32_e32 v126, 16, v67
	v_and_b32_e32 v127, 0xffff0000, v67
	v_pk_mul_f32 v[120:121], s[26:27], v[120:121] op_sel_hi:[0,1]
	v_pk_mul_f32 v[122:123], s[26:27], v[122:123] op_sel_hi:[0,1]
	v_pk_mul_f32 v[124:125], s[26:27], v[124:125] op_sel_hi:[0,1]
	v_pk_mul_f32 v[126:127], s[26:27], v[126:127] op_sel_hi:[0,1]
	v_pk_mul_f32 v[120:121], v[4:5], v[120:121]
	v_pk_mul_f32 v[122:123], v[6:7], v[122:123]
	v_pk_mul_f32 v[124:125], v[0:1], v[124:125]
	v_pk_mul_f32 v[126:127], v[2:3], v[126:127]
	global_store_dwordx4 v23, v[120:123], s[14:15] nt
	global_store_dwordx4 v23, v[124:127], s[14:15] offset:16 nt
	v_lshlrev_b32_e32 v136, 16, v68
	v_and_b32_e32 v137, 0xffff0000, v68
	v_lshlrev_b32_e32 v138, 16, v69
	v_and_b32_e32 v139, 0xffff0000, v69
	v_lshlrev_b32_e32 v140, 16, v70
	v_and_b32_e32 v141, 0xffff0000, v70
	v_lshlrev_b32_e32 v142, 16, v71
	v_and_b32_e32 v143, 0xffff0000, v71
	v_pk_mul_f32 v[136:137], s[26:27], v[136:137] op_sel_hi:[0,1]
	v_pk_mul_f32 v[138:139], s[26:27], v[138:139] op_sel_hi:[0,1]
	v_pk_mul_f32 v[140:141], s[26:27], v[140:141] op_sel_hi:[0,1]
	v_pk_mul_f32 v[142:143], s[26:27], v[142:143] op_sel_hi:[0,1]
	v_pk_mul_f32 v[136:137], v[12:13], v[136:137]
	v_pk_mul_f32 v[138:139], v[14:15], v[138:139]
	v_pk_mul_f32 v[140:141], v[8:9], v[140:141]
	v_pk_mul_f32 v[142:143], v[10:11], v[142:143]
	global_store_dwordx4 v23, v[136:139], s[14:15] offset:2048 nt
	global_store_dwordx4 v23, v[140:143], s[14:15] offset:2064 nt
	s_add_u32 s14, s14, 0x400000
	s_addc_u32 s15, s15, 0
	s_add_u32 s10, s10, 0x200000
	s_addc_u32 s11, s11, 0
	s_add_u32 s12, s12, 0x10000
	s_addc_u32 s13, s13, 0
	global_load_dword v72, v24, s[12:13]
	global_load_dwordx4 v[40:43], v16, s[10:11]
	global_load_dwordx4 v[44:47], v16, s[10:11] offset:1024
	global_load_dwordx4 v[48:51], v17, s[10:11]
	global_load_dwordx4 v[52:55], v17, s[10:11] offset:1024
	global_load_dwordx4 v[56:59], v18, s[10:11]
	global_load_dwordx4 v[60:63], v18, s[10:11] offset:1024
	global_load_dwordx4 v[64:67], v19, s[10:11]
	global_load_dwordx4 v[68:71], v19, s[10:11] offset:1024
	s_waitcnt vmcnt(33)
	v_add_f32_dpp v26, v112, v112 quad_perm:[1,0,3,2] row_mask:0xf bank_mask:0xf
	s_nop 1
	v_add_f32_dpp v27, v26, v26 quad_perm:[2,3,0,1] row_mask:0xf bank_mask:0xf
	s_nop 1
	v_add_f32_dpp v26, v27, v27 row_half_mirror row_mask:0xf bank_mask:0xf
	s_nop 1
	v_add_f32_dpp v30, v26, v26 row_mirror row_mask:0xf bank_mask:0xf
	v_fmamk_f32 v30, v30, 0x3a800000, v28
	v_mul_f32_e32 v31, 0x4f800000, v30
	v_cmp_gt_f32_e32 vcc, s5, v30
	s_nop 1
	v_cndmask_b32_e32 v30, v30, v31, vcc
	v_sqrt_f32_e32 v31, v30
	s_nop 0
	v_add_u32_e32 v36, -1, v31
	v_add_u32_e32 v37, 1, v31
	v_fma_f32 v38, -v36, v31, v30
	v_fma_f32 v39, -v37, v31, v30
	v_cmp_ge_f32_e64 s[2:3], 0, v38
	s_nop 1
	v_cndmask_b32_e64 v31, v31, v36, s[2:3]
	v_cmp_lt_f32_e64 s[2:3], 0, v39
	s_nop 1
	v_cndmask_b32_e64 v31, v31, v37, s[2:3]
	v_mul_f32_e32 v36, 0x37800000, v31
	v_cndmask_b32_e32 v31, v31, v36, vcc
	v_cmp_class_f32_e32 vcc, v30, v29
	s_nop 1
	v_cndmask_b32_e32 v30, v31, v30, vcc
	v_div_scale_f32 v31, s[2:3], v30, v30, 1.0
	v_rcp_f32_e32 v36, v31
	v_div_scale_f32 v37, vcc, 1.0, v30, 1.0
	v_fma_f32 v38, -v31, v36, 1.0
	v_fmac_f32_e32 v36, v38, v36
	v_mul_f32_e32 v38, v37, v36
	v_fma_f32 v39, -v31, v38, v37
	v_fmac_f32_e32 v38, v39, v36
	v_fma_f32 v31, -v31, v38, v37
	v_div_fmas_f32 v31, v31, v36, v38
	v_div_fixup_f32 v38, v31, v30, 1.0
	s_nop 1
	v_readlane_b32 s20, v38, 0
	v_readlane_b32 s22, v38, 16
	v_readlane_b32 s24, v38, 32
	v_readlane_b32 s26, v38, 48
	s_waitcnt vmcnt(25)
	v_lshlrev_b32_e32 v120, 16, v80
	v_and_b32_e32 v121, 0xffff0000, v80
	v_lshlrev_b32_e32 v122, 16, v81
	v_and_b32_e32 v123, 0xffff0000, v81
	v_lshlrev_b32_e32 v124, 16, v82
	v_and_b32_e32 v125, 0xffff0000, v82
	v_lshlrev_b32_e32 v126, 16, v83
	v_and_b32_e32 v127, 0xffff0000, v83
	v_pk_mul_f32 v[120:121], s[20:21], v[120:121] op_sel_hi:[0,1]
	v_pk_mul_f32 v[122:123], s[20:21], v[122:123] op_sel_hi:[0,1]
	v_pk_mul_f32 v[124:125], s[20:21], v[124:125] op_sel_hi:[0,1]
	v_pk_mul_f32 v[126:127], s[20:21], v[126:127] op_sel_hi:[0,1]
	v_pk_mul_f32 v[120:121], v[4:5], v[120:121]
	v_pk_mul_f32 v[122:123], v[6:7], v[122:123]
	v_pk_mul_f32 v[124:125], v[0:1], v[124:125]
	v_pk_mul_f32 v[126:127], v[2:3], v[126:127]
	global_store_dwordx4 v20, v[120:123], s[14:15] nt
	global_store_dwordx4 v20, v[124:127], s[14:15] offset:16 nt
	v_lshlrev_b32_e32 v136, 16, v84
	v_and_b32_e32 v137, 0xffff0000, v84
	v_lshlrev_b32_e32 v138, 16, v85
	v_and_b32_e32 v139, 0xffff0000, v85
	v_lshlrev_b32_e32 v140, 16, v86
	v_and_b32_e32 v141, 0xffff0000, v86
	v_lshlrev_b32_e32 v142, 16, v87
	v_and_b32_e32 v143, 0xffff0000, v87
	v_pk_mul_f32 v[136:137], s[20:21], v[136:137] op_sel_hi:[0,1]
	v_pk_mul_f32 v[138:139], s[20:21], v[138:139] op_sel_hi:[0,1]
	v_pk_mul_f32 v[140:141], s[20:21], v[140:141] op_sel_hi:[0,1]
	v_pk_mul_f32 v[142:143], s[20:21], v[142:143] op_sel_hi:[0,1]
	v_pk_mul_f32 v[136:137], v[12:13], v[136:137]
	v_pk_mul_f32 v[138:139], v[14:15], v[138:139]
	v_pk_mul_f32 v[140:141], v[8:9], v[140:141]
	v_pk_mul_f32 v[142:143], v[10:11], v[142:143]
	global_store_dwordx4 v20, v[136:139], s[14:15] offset:2048 nt
	global_store_dwordx4 v20, v[140:143], s[14:15] offset:2064 nt
	v_lshlrev_b32_e32 v120, 16, v88
	v_and_b32_e32 v121, 0xffff0000, v88
	v_lshlrev_b32_e32 v122, 16, v89
	v_and_b32_e32 v123, 0xffff0000, v89
	v_lshlrev_b32_e32 v124, 16, v90
	v_and_b32_e32 v125, 0xffff0000, v90
	v_lshlrev_b32_e32 v126, 16, v91
	v_and_b32_e32 v127, 0xffff0000, v91
	v_pk_mul_f32 v[120:121], s[22:23], v[120:121] op_sel_hi:[0,1]
	v_pk_mul_f32 v[122:123], s[22:23], v[122:123] op_sel_hi:[0,1]
	v_pk_mul_f32 v[124:125], s[22:23], v[124:125] op_sel_hi:[0,1]
	v_pk_mul_f32 v[126:127], s[22:23], v[126:127] op_sel_hi:[0,1]
	v_pk_mul_f32 v[120:121], v[4:5], v[120:121]
	v_pk_mul_f32 v[122:123], v[6:7], v[122:123]
	v_pk_mul_f32 v[124:125], v[0:1], v[124:125]
	v_pk_mul_f32 v[126:127], v[2:3], v[126:127]
	global_store_dwordx4 v21, v[120:123], s[14:15] nt
	global_store_dwordx4 v21, v[124:127], s[14:15] offset:16 nt
	v_lshlrev_b32_e32 v136, 16, v92
	v_and_b32_e32 v137, 0xffff0000, v92
	v_lshlrev_b32_e32 v138, 16, v93
	v_and_b32_e32 v139, 0xffff0000, v93
	v_lshlrev_b32_e32 v140, 16, v94
	v_and_b32_e32 v141, 0xffff0000, v94
	v_lshlrev_b32_e32 v142, 16, v95
	v_and_b32_e32 v143, 0xffff0000, v95
	v_pk_mul_f32 v[136:137], s[22:23], v[136:137] op_sel_hi:[0,1]
	v_pk_mul_f32 v[138:139], s[22:23], v[138:139] op_sel_hi:[0,1]
	v_pk_mul_f32 v[140:141], s[22:23], v[140:141] op_sel_hi:[0,1]
	v_pk_mul_f32 v[142:143], s[22:23], v[142:143] op_sel_hi:[0,1]
	v_pk_mul_f32 v[136:137], v[12:13], v[136:137]
	v_pk_mul_f32 v[138:139], v[14:15], v[138:139]
	v_pk_mul_f32 v[140:141], v[8:9], v[140:141]
	v_pk_mul_f32 v[142:143], v[10:11], v[142:143]
	global_store_dwordx4 v21, v[136:139], s[14:15] offset:2048 nt
	global_store_dwordx4 v21, v[140:143], s[14:15] offset:2064 nt
	v_lshlrev_b32_e32 v120, 16, v96
	v_and_b32_e32 v121, 0xffff0000, v96
	v_lshlrev_b32_e32 v122, 16, v97
	v_and_b32_e32 v123, 0xffff0000, v97
	v_lshlrev_b32_e32 v124, 16, v98
	v_and_b32_e32 v125, 0xffff0000, v98
	v_lshlrev_b32_e32 v126, 16, v99
	v_and_b32_e32 v127, 0xffff0000, v99
	v_pk_mul_f32 v[120:121], s[24:25], v[120:121] op_sel_hi:[0,1]
	v_pk_mul_f32 v[122:123], s[24:25], v[122:123] op_sel_hi:[0,1]
	v_pk_mul_f32 v[124:125], s[24:25], v[124:125] op_sel_hi:[0,1]
	v_pk_mul_f32 v[126:127], s[24:25], v[126:127] op_sel_hi:[0,1]
	v_pk_mul_f32 v[120:121], v[4:5], v[120:121]
	v_pk_mul_f32 v[122:123], v[6:7], v[122:123]
	v_pk_mul_f32 v[124:125], v[0:1], v[124:125]
	v_pk_mul_f32 v[126:127], v[2:3], v[126:127]
	global_store_dwordx4 v22, v[120:123], s[14:15] nt
	global_store_dwordx4 v22, v[124:127], s[14:15] offset:16 nt
	v_lshlrev_b32_e32 v136, 16, v100
	v_and_b32_e32 v137, 0xffff0000, v100
	v_lshlrev_b32_e32 v138, 16, v101
	v_and_b32_e32 v139, 0xffff0000, v101
	v_lshlrev_b32_e32 v140, 16, v102
	v_and_b32_e32 v141, 0xffff0000, v102
	v_lshlrev_b32_e32 v142, 16, v103
	v_and_b32_e32 v143, 0xffff0000, v103
	v_pk_mul_f32 v[136:137], s[24:25], v[136:137] op_sel_hi:[0,1]
	v_pk_mul_f32 v[138:139], s[24:25], v[138:139] op_sel_hi:[0,1]
	v_pk_mul_f32 v[140:141], s[24:25], v[140:141] op_sel_hi:[0,1]
	v_pk_mul_f32 v[142:143], s[24:25], v[142:143] op_sel_hi:[0,1]
	v_pk_mul_f32 v[136:137], v[12:13], v[136:137]
	v_pk_mul_f32 v[138:139], v[14:15], v[138:139]
	v_pk_mul_f32 v[140:141], v[8:9], v[140:141]
	v_pk_mul_f32 v[142:143], v[10:11], v[142:143]
	global_store_dwordx4 v22, v[136:139], s[14:15] offset:2048 nt
	global_store_dwordx4 v22, v[140:143], s[14:15] offset:2064 nt
	v_lshlrev_b32_e32 v120, 16, v104
	v_and_b32_e32 v121, 0xffff0000, v104
	v_lshlrev_b32_e32 v122, 16, v105
	v_and_b32_e32 v123, 0xffff0000, v105
	v_lshlrev_b32_e32 v124, 16, v106
	v_and_b32_e32 v125, 0xffff0000, v106
	v_lshlrev_b32_e32 v126, 16, v107
	v_and_b32_e32 v127, 0xffff0000, v107
	v_pk_mul_f32 v[120:121], s[26:27], v[120:121] op_sel_hi:[0,1]
	v_pk_mul_f32 v[122:123], s[26:27], v[122:123] op_sel_hi:[0,1]
	v_pk_mul_f32 v[124:125], s[26:27], v[124:125] op_sel_hi:[0,1]
	v_pk_mul_f32 v[126:127], s[26:27], v[126:127] op_sel_hi:[0,1]
	v_pk_mul_f32 v[120:121], v[4:5], v[120:121]
	v_pk_mul_f32 v[122:123], v[6:7], v[122:123]
	v_pk_mul_f32 v[124:125], v[0:1], v[124:125]
	v_pk_mul_f32 v[126:127], v[2:3], v[126:127]
	global_store_dwordx4 v23, v[120:123], s[14:15] nt
	global_store_dwordx4 v23, v[124:127], s[14:15] offset:16 nt
	v_lshlrev_b32_e32 v136, 16, v108
	v_and_b32_e32 v137, 0xffff0000, v108
	v_lshlrev_b32_e32 v138, 16, v109
	v_and_b32_e32 v139, 0xffff0000, v109
	v_lshlrev_b32_e32 v140, 16, v110
	v_and_b32_e32 v141, 0xffff0000, v110
	v_lshlrev_b32_e32 v142, 16, v111
	v_and_b32_e32 v143, 0xffff0000, v111
	v_pk_mul_f32 v[136:137], s[26:27], v[136:137] op_sel_hi:[0,1]
	v_pk_mul_f32 v[138:139], s[26:27], v[138:139] op_sel_hi:[0,1]
	v_pk_mul_f32 v[140:141], s[26:27], v[140:141] op_sel_hi:[0,1]
	v_pk_mul_f32 v[142:143], s[26:27], v[142:143] op_sel_hi:[0,1]
	v_pk_mul_f32 v[136:137], v[12:13], v[136:137]
	v_pk_mul_f32 v[138:139], v[14:15], v[138:139]
	v_pk_mul_f32 v[140:141], v[8:9], v[140:141]
	v_pk_mul_f32 v[142:143], v[10:11], v[142:143]
	global_store_dwordx4 v23, v[136:139], s[14:15] offset:2048 nt
	global_store_dwordx4 v23, v[140:143], s[14:15] offset:2064 nt
	s_add_u32 s14, s14, 0x400000
	s_addc_u32 s15, s15, 0
	s_add_u32 s10, s10, 0x200000
	s_addc_u32 s11, s11, 0
	s_add_u32 s12, s12, 0x10000
	s_addc_u32 s13, s13, 0
	global_load_dword v112, v24, s[12:13]
	global_load_dwordx4 v[80:83], v16, s[10:11]
	global_load_dwordx4 v[84:87], v16, s[10:11] offset:1024
	global_load_dwordx4 v[88:91], v17, s[10:11]
	global_load_dwordx4 v[92:95], v17, s[10:11] offset:1024
	global_load_dwordx4 v[96:99], v18, s[10:11]
	global_load_dwordx4 v[100:103], v18, s[10:11] offset:1024
	global_load_dwordx4 v[104:107], v19, s[10:11]
	global_load_dwordx4 v[108:111], v19, s[10:11] offset:1024
	s_waitcnt vmcnt(33)
	v_add_f32_dpp v26, v72, v72 quad_perm:[1,0,3,2] row_mask:0xf bank_mask:0xf
	s_nop 1
	v_add_f32_dpp v27, v26, v26 quad_perm:[2,3,0,1] row_mask:0xf bank_mask:0xf
	s_nop 1
	v_add_f32_dpp v26, v27, v27 row_half_mirror row_mask:0xf bank_mask:0xf
	s_nop 1
	v_add_f32_dpp v30, v26, v26 row_mirror row_mask:0xf bank_mask:0xf
	v_fmamk_f32 v30, v30, 0x3a800000, v28
	v_mul_f32_e32 v31, 0x4f800000, v30
	v_cmp_gt_f32_e32 vcc, s5, v30
	s_nop 1
	v_cndmask_b32_e32 v30, v30, v31, vcc
	v_sqrt_f32_e32 v31, v30
	s_nop 0
	v_add_u32_e32 v36, -1, v31
	v_add_u32_e32 v37, 1, v31
	v_fma_f32 v38, -v36, v31, v30
	v_fma_f32 v39, -v37, v31, v30
	v_cmp_ge_f32_e64 s[2:3], 0, v38
	s_nop 1
	v_cndmask_b32_e64 v31, v31, v36, s[2:3]
	v_cmp_lt_f32_e64 s[2:3], 0, v39
	s_nop 1
	v_cndmask_b32_e64 v31, v31, v37, s[2:3]
	v_mul_f32_e32 v36, 0x37800000, v31
	v_cndmask_b32_e32 v31, v31, v36, vcc
	v_cmp_class_f32_e32 vcc, v30, v29
	s_nop 1
	v_cndmask_b32_e32 v30, v31, v30, vcc
	v_div_scale_f32 v31, s[2:3], v30, v30, 1.0
	v_rcp_f32_e32 v36, v31
	v_div_scale_f32 v37, vcc, 1.0, v30, 1.0
	v_fma_f32 v38, -v31, v36, 1.0
	v_fmac_f32_e32 v36, v38, v36
	v_mul_f32_e32 v38, v37, v36
	v_fma_f32 v39, -v31, v38, v37
	v_fmac_f32_e32 v38, v39, v36
	v_fma_f32 v31, -v31, v38, v37
	v_div_fmas_f32 v31, v31, v36, v38
	v_div_fixup_f32 v38, v31, v30, 1.0
	s_nop 1
	v_readlane_b32 s20, v38, 0
	v_readlane_b32 s22, v38, 16
	v_readlane_b32 s24, v38, 32
	v_readlane_b32 s26, v38, 48
	s_waitcnt vmcnt(25)
	v_lshlrev_b32_e32 v120, 16, v40
	v_and_b32_e32 v121, 0xffff0000, v40
	v_lshlrev_b32_e32 v122, 16, v41
	v_and_b32_e32 v123, 0xffff0000, v41
	v_lshlrev_b32_e32 v124, 16, v42
	v_and_b32_e32 v125, 0xffff0000, v42
	v_lshlrev_b32_e32 v126, 16, v43
	v_and_b32_e32 v127, 0xffff0000, v43
	v_pk_mul_f32 v[120:121], s[20:21], v[120:121] op_sel_hi:[0,1]
	v_pk_mul_f32 v[122:123], s[20:21], v[122:123] op_sel_hi:[0,1]
	v_pk_mul_f32 v[124:125], s[20:21], v[124:125] op_sel_hi:[0,1]
	v_pk_mul_f32 v[126:127], s[20:21], v[126:127] op_sel_hi:[0,1]
	v_pk_mul_f32 v[120:121], v[4:5], v[120:121]
	v_pk_mul_f32 v[122:123], v[6:7], v[122:123]
	v_pk_mul_f32 v[124:125], v[0:1], v[124:125]
	v_pk_mul_f32 v[126:127], v[2:3], v[126:127]
	global_store_dwordx4 v20, v[120:123], s[14:15] nt
	global_store_dwordx4 v20, v[124:127], s[14:15] offset:16 nt
	v_lshlrev_b32_e32 v136, 16, v44
	v_and_b32_e32 v137, 0xffff0000, v44
	v_lshlrev_b32_e32 v138, 16, v45
	v_and_b32_e32 v139, 0xffff0000, v45
	v_lshlrev_b32_e32 v140, 16, v46
	v_and_b32_e32 v141, 0xffff0000, v46
	v_lshlrev_b32_e32 v142, 16, v47
	v_and_b32_e32 v143, 0xffff0000, v47
	v_pk_mul_f32 v[136:137], s[20:21], v[136:137] op_sel_hi:[0,1]
	v_pk_mul_f32 v[138:139], s[20:21], v[138:139] op_sel_hi:[0,1]
	v_pk_mul_f32 v[140:141], s[20:21], v[140:141] op_sel_hi:[0,1]
	v_pk_mul_f32 v[142:143], s[20:21], v[142:143] op_sel_hi:[0,1]
	v_pk_mul_f32 v[136:137], v[12:13], v[136:137]
	v_pk_mul_f32 v[138:139], v[14:15], v[138:139]
	v_pk_mul_f32 v[140:141], v[8:9], v[140:141]
	v_pk_mul_f32 v[142:143], v[10:11], v[142:143]
	global_store_dwordx4 v20, v[136:139], s[14:15] offset:2048 nt
	global_store_dwordx4 v20, v[140:143], s[14:15] offset:2064 nt
	v_lshlrev_b32_e32 v120, 16, v48
	v_and_b32_e32 v121, 0xffff0000, v48
	v_lshlrev_b32_e32 v122, 16, v49
	v_and_b32_e32 v123, 0xffff0000, v49
	v_lshlrev_b32_e32 v124, 16, v50
	v_and_b32_e32 v125, 0xffff0000, v50
	v_lshlrev_b32_e32 v126, 16, v51
	v_and_b32_e32 v127, 0xffff0000, v51
	v_pk_mul_f32 v[120:121], s[22:23], v[120:121] op_sel_hi:[0,1]
	v_pk_mul_f32 v[122:123], s[22:23], v[122:123] op_sel_hi:[0,1]
	v_pk_mul_f32 v[124:125], s[22:23], v[124:125] op_sel_hi:[0,1]
	v_pk_mul_f32 v[126:127], s[22:23], v[126:127] op_sel_hi:[0,1]
	v_pk_mul_f32 v[120:121], v[4:5], v[120:121]
	v_pk_mul_f32 v[122:123], v[6:7], v[122:123]
	v_pk_mul_f32 v[124:125], v[0:1], v[124:125]
	v_pk_mul_f32 v[126:127], v[2:3], v[126:127]
	global_store_dwordx4 v21, v[120:123], s[14:15] nt
	global_store_dwordx4 v21, v[124:127], s[14:15] offset:16 nt
	v_lshlrev_b32_e32 v136, 16, v52
	v_and_b32_e32 v137, 0xffff0000, v52
	v_lshlrev_b32_e32 v138, 16, v53
	v_and_b32_e32 v139, 0xffff0000, v53
	v_lshlrev_b32_e32 v140, 16, v54
	v_and_b32_e32 v141, 0xffff0000, v54
	v_lshlrev_b32_e32 v142, 16, v55
	v_and_b32_e32 v143, 0xffff0000, v55
	v_pk_mul_f32 v[136:137], s[22:23], v[136:137] op_sel_hi:[0,1]
	v_pk_mul_f32 v[138:139], s[22:23], v[138:139] op_sel_hi:[0,1]
	v_pk_mul_f32 v[140:141], s[22:23], v[140:141] op_sel_hi:[0,1]
	v_pk_mul_f32 v[142:143], s[22:23], v[142:143] op_sel_hi:[0,1]
	v_pk_mul_f32 v[136:137], v[12:13], v[136:137]
	v_pk_mul_f32 v[138:139], v[14:15], v[138:139]
	v_pk_mul_f32 v[140:141], v[8:9], v[140:141]
	v_pk_mul_f32 v[142:143], v[10:11], v[142:143]
	global_store_dwordx4 v21, v[136:139], s[14:15] offset:2048 nt
	global_store_dwordx4 v21, v[140:143], s[14:15] offset:2064 nt
	v_lshlrev_b32_e32 v120, 16, v56
	v_and_b32_e32 v121, 0xffff0000, v56
	v_lshlrev_b32_e32 v122, 16, v57
	v_and_b32_e32 v123, 0xffff0000, v57
	v_lshlrev_b32_e32 v124, 16, v58
	v_and_b32_e32 v125, 0xffff0000, v58
	v_lshlrev_b32_e32 v126, 16, v59
	v_and_b32_e32 v127, 0xffff0000, v59
	v_pk_mul_f32 v[120:121], s[24:25], v[120:121] op_sel_hi:[0,1]
	v_pk_mul_f32 v[122:123], s[24:25], v[122:123] op_sel_hi:[0,1]
	v_pk_mul_f32 v[124:125], s[24:25], v[124:125] op_sel_hi:[0,1]
	v_pk_mul_f32 v[126:127], s[24:25], v[126:127] op_sel_hi:[0,1]
	v_pk_mul_f32 v[120:121], v[4:5], v[120:121]
	v_pk_mul_f32 v[122:123], v[6:7], v[122:123]
	v_pk_mul_f32 v[124:125], v[0:1], v[124:125]
	v_pk_mul_f32 v[126:127], v[2:3], v[126:127]
	global_store_dwordx4 v22, v[120:123], s[14:15] nt
	global_store_dwordx4 v22, v[124:127], s[14:15] offset:16 nt
	v_lshlrev_b32_e32 v136, 16, v60
	v_and_b32_e32 v137, 0xffff0000, v60
	v_lshlrev_b32_e32 v138, 16, v61
	v_and_b32_e32 v139, 0xffff0000, v61
	v_lshlrev_b32_e32 v140, 16, v62
	v_and_b32_e32 v141, 0xffff0000, v62
	v_lshlrev_b32_e32 v142, 16, v63
	v_and_b32_e32 v143, 0xffff0000, v63
	v_pk_mul_f32 v[136:137], s[24:25], v[136:137] op_sel_hi:[0,1]
	v_pk_mul_f32 v[138:139], s[24:25], v[138:139] op_sel_hi:[0,1]
	v_pk_mul_f32 v[140:141], s[24:25], v[140:141] op_sel_hi:[0,1]
	v_pk_mul_f32 v[142:143], s[24:25], v[142:143] op_sel_hi:[0,1]
	v_pk_mul_f32 v[136:137], v[12:13], v[136:137]
	v_pk_mul_f32 v[138:139], v[14:15], v[138:139]
	v_pk_mul_f32 v[140:141], v[8:9], v[140:141]
	v_pk_mul_f32 v[142:143], v[10:11], v[142:143]
	global_store_dwordx4 v22, v[136:139], s[14:15] offset:2048 nt
	global_store_dwordx4 v22, v[140:143], s[14:15] offset:2064 nt
	v_lshlrev_b32_e32 v120, 16, v64
	v_and_b32_e32 v121, 0xffff0000, v64
	v_lshlrev_b32_e32 v122, 16, v65
	v_and_b32_e32 v123, 0xffff0000, v65
	v_lshlrev_b32_e32 v124, 16, v66
	v_and_b32_e32 v125, 0xffff0000, v66
	v_lshlrev_b32_e32 v126, 16, v67
	v_and_b32_e32 v127, 0xffff0000, v67
	v_pk_mul_f32 v[120:121], s[26:27], v[120:121] op_sel_hi:[0,1]
	v_pk_mul_f32 v[122:123], s[26:27], v[122:123] op_sel_hi:[0,1]
	v_pk_mul_f32 v[124:125], s[26:27], v[124:125] op_sel_hi:[0,1]
	v_pk_mul_f32 v[126:127], s[26:27], v[126:127] op_sel_hi:[0,1]
	v_pk_mul_f32 v[120:121], v[4:5], v[120:121]
	v_pk_mul_f32 v[122:123], v[6:7], v[122:123]
	v_pk_mul_f32 v[124:125], v[0:1], v[124:125]
	v_pk_mul_f32 v[126:127], v[2:3], v[126:127]
	global_store_dwordx4 v23, v[120:123], s[14:15] nt
	global_store_dwordx4 v23, v[124:127], s[14:15] offset:16 nt
	v_lshlrev_b32_e32 v136, 16, v68
	v_and_b32_e32 v137, 0xffff0000, v68
	v_lshlrev_b32_e32 v138, 16, v69
	v_and_b32_e32 v139, 0xffff0000, v69
	v_lshlrev_b32_e32 v140, 16, v70
	v_and_b32_e32 v141, 0xffff0000, v70
	v_lshlrev_b32_e32 v142, 16, v71
	v_and_b32_e32 v143, 0xffff0000, v71
	v_pk_mul_f32 v[136:137], s[26:27], v[136:137] op_sel_hi:[0,1]
	v_pk_mul_f32 v[138:139], s[26:27], v[138:139] op_sel_hi:[0,1]
	v_pk_mul_f32 v[140:141], s[26:27], v[140:141] op_sel_hi:[0,1]
	v_pk_mul_f32 v[142:143], s[26:27], v[142:143] op_sel_hi:[0,1]
	v_pk_mul_f32 v[136:137], v[12:13], v[136:137]
	v_pk_mul_f32 v[138:139], v[14:15], v[138:139]
	v_pk_mul_f32 v[140:141], v[8:9], v[140:141]
	v_pk_mul_f32 v[142:143], v[10:11], v[142:143]
	global_store_dwordx4 v23, v[136:139], s[14:15] offset:2048 nt
	global_store_dwordx4 v23, v[140:143], s[14:15] offset:2064 nt
	s_add_u32 s14, s14, 0x400000
	s_addc_u32 s15, s15, 0
	s_add_u32 s10, s10, 0x200000
	s_addc_u32 s11, s11, 0
	s_add_u32 s12, s12, 0x10000
	s_addc_u32 s13, s13, 0
	global_load_dword v72, v24, s[12:13]
	global_load_dwordx4 v[40:43], v16, s[10:11]
	global_load_dwordx4 v[44:47], v16, s[10:11] offset:1024
	global_load_dwordx4 v[48:51], v17, s[10:11]
	global_load_dwordx4 v[52:55], v17, s[10:11] offset:1024
	global_load_dwordx4 v[56:59], v18, s[10:11]
	global_load_dwordx4 v[60:63], v18, s[10:11] offset:1024
	global_load_dwordx4 v[64:67], v19, s[10:11]
	global_load_dwordx4 v[68:71], v19, s[10:11] offset:1024
	s_waitcnt vmcnt(33)
	v_add_f32_dpp v26, v112, v112 quad_perm:[1,0,3,2] row_mask:0xf bank_mask:0xf
	s_nop 1
	v_add_f32_dpp v27, v26, v26 quad_perm:[2,3,0,1] row_mask:0xf bank_mask:0xf
	s_nop 1
	v_add_f32_dpp v26, v27, v27 row_half_mirror row_mask:0xf bank_mask:0xf
	s_nop 1
	v_add_f32_dpp v30, v26, v26 row_mirror row_mask:0xf bank_mask:0xf
	v_fmamk_f32 v30, v30, 0x3a800000, v28
	v_mul_f32_e32 v31, 0x4f800000, v30
	v_cmp_gt_f32_e32 vcc, s5, v30
	s_nop 1
	v_cndmask_b32_e32 v30, v30, v31, vcc
	v_sqrt_f32_e32 v31, v30
	s_nop 0
	v_add_u32_e32 v36, -1, v31
	v_add_u32_e32 v37, 1, v31
	v_fma_f32 v38, -v36, v31, v30
	v_fma_f32 v39, -v37, v31, v30
	v_cmp_ge_f32_e64 s[2:3], 0, v38
	s_nop 1
	v_cndmask_b32_e64 v31, v31, v36, s[2:3]
	v_cmp_lt_f32_e64 s[2:3], 0, v39
	s_nop 1
	v_cndmask_b32_e64 v31, v31, v37, s[2:3]
	v_mul_f32_e32 v36, 0x37800000, v31
	v_cndmask_b32_e32 v31, v31, v36, vcc
	v_cmp_class_f32_e32 vcc, v30, v29
	s_nop 1
	v_cndmask_b32_e32 v30, v31, v30, vcc
	v_div_scale_f32 v31, s[2:3], v30, v30, 1.0
	v_rcp_f32_e32 v36, v31
	v_div_scale_f32 v37, vcc, 1.0, v30, 1.0
	v_fma_f32 v38, -v31, v36, 1.0
	v_fmac_f32_e32 v36, v38, v36
	v_mul_f32_e32 v38, v37, v36
	v_fma_f32 v39, -v31, v38, v37
	v_fmac_f32_e32 v38, v39, v36
	v_fma_f32 v31, -v31, v38, v37
	v_div_fmas_f32 v31, v31, v36, v38
	v_div_fixup_f32 v38, v31, v30, 1.0
	s_nop 1
	v_readlane_b32 s20, v38, 0
	v_readlane_b32 s22, v38, 16
	v_readlane_b32 s24, v38, 32
	v_readlane_b32 s26, v38, 48
	s_waitcnt vmcnt(25)
	v_lshlrev_b32_e32 v120, 16, v80
	v_and_b32_e32 v121, 0xffff0000, v80
	v_lshlrev_b32_e32 v122, 16, v81
	v_and_b32_e32 v123, 0xffff0000, v81
	v_lshlrev_b32_e32 v124, 16, v82
	v_and_b32_e32 v125, 0xffff0000, v82
	v_lshlrev_b32_e32 v126, 16, v83
	v_and_b32_e32 v127, 0xffff0000, v83
	v_pk_mul_f32 v[120:121], s[20:21], v[120:121] op_sel_hi:[0,1]
	v_pk_mul_f32 v[122:123], s[20:21], v[122:123] op_sel_hi:[0,1]
	v_pk_mul_f32 v[124:125], s[20:21], v[124:125] op_sel_hi:[0,1]
	v_pk_mul_f32 v[126:127], s[20:21], v[126:127] op_sel_hi:[0,1]
	v_pk_mul_f32 v[120:121], v[4:5], v[120:121]
	v_pk_mul_f32 v[122:123], v[6:7], v[122:123]
	v_pk_mul_f32 v[124:125], v[0:1], v[124:125]
	v_pk_mul_f32 v[126:127], v[2:3], v[126:127]
	global_store_dwordx4 v20, v[120:123], s[14:15] nt
	global_store_dwordx4 v20, v[124:127], s[14:15] offset:16 nt
	v_lshlrev_b32_e32 v136, 16, v84
	v_and_b32_e32 v137, 0xffff0000, v84
	v_lshlrev_b32_e32 v138, 16, v85
	v_and_b32_e32 v139, 0xffff0000, v85
	v_lshlrev_b32_e32 v140, 16, v86
	v_and_b32_e32 v141, 0xffff0000, v86
	v_lshlrev_b32_e32 v142, 16, v87
	v_and_b32_e32 v143, 0xffff0000, v87
	v_pk_mul_f32 v[136:137], s[20:21], v[136:137] op_sel_hi:[0,1]
	v_pk_mul_f32 v[138:139], s[20:21], v[138:139] op_sel_hi:[0,1]
	v_pk_mul_f32 v[140:141], s[20:21], v[140:141] op_sel_hi:[0,1]
	v_pk_mul_f32 v[142:143], s[20:21], v[142:143] op_sel_hi:[0,1]
	v_pk_mul_f32 v[136:137], v[12:13], v[136:137]
	v_pk_mul_f32 v[138:139], v[14:15], v[138:139]
	v_pk_mul_f32 v[140:141], v[8:9], v[140:141]
	v_pk_mul_f32 v[142:143], v[10:11], v[142:143]
	global_store_dwordx4 v20, v[136:139], s[14:15] offset:2048 nt
	global_store_dwordx4 v20, v[140:143], s[14:15] offset:2064 nt
	v_lshlrev_b32_e32 v120, 16, v88
	v_and_b32_e32 v121, 0xffff0000, v88
	v_lshlrev_b32_e32 v122, 16, v89
	v_and_b32_e32 v123, 0xffff0000, v89
	v_lshlrev_b32_e32 v124, 16, v90
	v_and_b32_e32 v125, 0xffff0000, v90
	v_lshlrev_b32_e32 v126, 16, v91
	v_and_b32_e32 v127, 0xffff0000, v91
	v_pk_mul_f32 v[120:121], s[22:23], v[120:121] op_sel_hi:[0,1]
	v_pk_mul_f32 v[122:123], s[22:23], v[122:123] op_sel_hi:[0,1]
	v_pk_mul_f32 v[124:125], s[22:23], v[124:125] op_sel_hi:[0,1]
	v_pk_mul_f32 v[126:127], s[22:23], v[126:127] op_sel_hi:[0,1]
	v_pk_mul_f32 v[120:121], v[4:5], v[120:121]
	v_pk_mul_f32 v[122:123], v[6:7], v[122:123]
	v_pk_mul_f32 v[124:125], v[0:1], v[124:125]
	v_pk_mul_f32 v[126:127], v[2:3], v[126:127]
	global_store_dwordx4 v21, v[120:123], s[14:15] nt
	global_store_dwordx4 v21, v[124:127], s[14:15] offset:16 nt
	v_lshlrev_b32_e32 v136, 16, v92
	v_and_b32_e32 v137, 0xffff0000, v92
	v_lshlrev_b32_e32 v138, 16, v93
	v_and_b32_e32 v139, 0xffff0000, v93
	v_lshlrev_b32_e32 v140, 16, v94
	v_and_b32_e32 v141, 0xffff0000, v94
	v_lshlrev_b32_e32 v142, 16, v95
	v_and_b32_e32 v143, 0xffff0000, v95
	v_pk_mul_f32 v[136:137], s[22:23], v[136:137] op_sel_hi:[0,1]
	v_pk_mul_f32 v[138:139], s[22:23], v[138:139] op_sel_hi:[0,1]
	v_pk_mul_f32 v[140:141], s[22:23], v[140:141] op_sel_hi:[0,1]
	v_pk_mul_f32 v[142:143], s[22:23], v[142:143] op_sel_hi:[0,1]
	v_pk_mul_f32 v[136:137], v[12:13], v[136:137]
	v_pk_mul_f32 v[138:139], v[14:15], v[138:139]
	v_pk_mul_f32 v[140:141], v[8:9], v[140:141]
	v_pk_mul_f32 v[142:143], v[10:11], v[142:143]
	global_store_dwordx4 v21, v[136:139], s[14:15] offset:2048 nt
	global_store_dwordx4 v21, v[140:143], s[14:15] offset:2064 nt
	v_lshlrev_b32_e32 v120, 16, v96
	v_and_b32_e32 v121, 0xffff0000, v96
	v_lshlrev_b32_e32 v122, 16, v97
	v_and_b32_e32 v123, 0xffff0000, v97
	v_lshlrev_b32_e32 v124, 16, v98
	v_and_b32_e32 v125, 0xffff0000, v98
	v_lshlrev_b32_e32 v126, 16, v99
	v_and_b32_e32 v127, 0xffff0000, v99
	v_pk_mul_f32 v[120:121], s[24:25], v[120:121] op_sel_hi:[0,1]
	v_pk_mul_f32 v[122:123], s[24:25], v[122:123] op_sel_hi:[0,1]
	v_pk_mul_f32 v[124:125], s[24:25], v[124:125] op_sel_hi:[0,1]
	v_pk_mul_f32 v[126:127], s[24:25], v[126:127] op_sel_hi:[0,1]
	v_pk_mul_f32 v[120:121], v[4:5], v[120:121]
	v_pk_mul_f32 v[122:123], v[6:7], v[122:123]
	v_pk_mul_f32 v[124:125], v[0:1], v[124:125]
	v_pk_mul_f32 v[126:127], v[2:3], v[126:127]
	global_store_dwordx4 v22, v[120:123], s[14:15] nt
	global_store_dwordx4 v22, v[124:127], s[14:15] offset:16 nt
	v_lshlrev_b32_e32 v136, 16, v100
	v_and_b32_e32 v137, 0xffff0000, v100
	v_lshlrev_b32_e32 v138, 16, v101
	v_and_b32_e32 v139, 0xffff0000, v101
	v_lshlrev_b32_e32 v140, 16, v102
	v_and_b32_e32 v141, 0xffff0000, v102
	v_lshlrev_b32_e32 v142, 16, v103
	v_and_b32_e32 v143, 0xffff0000, v103
	v_pk_mul_f32 v[136:137], s[24:25], v[136:137] op_sel_hi:[0,1]
	v_pk_mul_f32 v[138:139], s[24:25], v[138:139] op_sel_hi:[0,1]
	v_pk_mul_f32 v[140:141], s[24:25], v[140:141] op_sel_hi:[0,1]
	v_pk_mul_f32 v[142:143], s[24:25], v[142:143] op_sel_hi:[0,1]
	v_pk_mul_f32 v[136:137], v[12:13], v[136:137]
	v_pk_mul_f32 v[138:139], v[14:15], v[138:139]
	v_pk_mul_f32 v[140:141], v[8:9], v[140:141]
	v_pk_mul_f32 v[142:143], v[10:11], v[142:143]
	global_store_dwordx4 v22, v[136:139], s[14:15] offset:2048 nt
	global_store_dwordx4 v22, v[140:143], s[14:15] offset:2064 nt
	v_lshlrev_b32_e32 v120, 16, v104
	v_and_b32_e32 v121, 0xffff0000, v104
	v_lshlrev_b32_e32 v122, 16, v105
	v_and_b32_e32 v123, 0xffff0000, v105
	v_lshlrev_b32_e32 v124, 16, v106
	v_and_b32_e32 v125, 0xffff0000, v106
	v_lshlrev_b32_e32 v126, 16, v107
	v_and_b32_e32 v127, 0xffff0000, v107
	v_pk_mul_f32 v[120:121], s[26:27], v[120:121] op_sel_hi:[0,1]
	v_pk_mul_f32 v[122:123], s[26:27], v[122:123] op_sel_hi:[0,1]
	v_pk_mul_f32 v[124:125], s[26:27], v[124:125] op_sel_hi:[0,1]
	v_pk_mul_f32 v[126:127], s[26:27], v[126:127] op_sel_hi:[0,1]
	v_pk_mul_f32 v[120:121], v[4:5], v[120:121]
	v_pk_mul_f32 v[122:123], v[6:7], v[122:123]
	v_pk_mul_f32 v[124:125], v[0:1], v[124:125]
	v_pk_mul_f32 v[126:127], v[2:3], v[126:127]
	global_store_dwordx4 v23, v[120:123], s[14:15] nt
	global_store_dwordx4 v23, v[124:127], s[14:15] offset:16 nt
	v_lshlrev_b32_e32 v136, 16, v108
	v_and_b32_e32 v137, 0xffff0000, v108
	v_lshlrev_b32_e32 v138, 16, v109
	v_and_b32_e32 v139, 0xffff0000, v109
	v_lshlrev_b32_e32 v140, 16, v110
	v_and_b32_e32 v141, 0xffff0000, v110
	v_lshlrev_b32_e32 v142, 16, v111
	v_and_b32_e32 v143, 0xffff0000, v111
	v_pk_mul_f32 v[136:137], s[26:27], v[136:137] op_sel_hi:[0,1]
	v_pk_mul_f32 v[138:139], s[26:27], v[138:139] op_sel_hi:[0,1]
	v_pk_mul_f32 v[140:141], s[26:27], v[140:141] op_sel_hi:[0,1]
	v_pk_mul_f32 v[142:143], s[26:27], v[142:143] op_sel_hi:[0,1]
	v_pk_mul_f32 v[136:137], v[12:13], v[136:137]
	v_pk_mul_f32 v[138:139], v[14:15], v[138:139]
	v_pk_mul_f32 v[140:141], v[8:9], v[140:141]
	v_pk_mul_f32 v[142:143], v[10:11], v[142:143]
	global_store_dwordx4 v23, v[136:139], s[14:15] offset:2048 nt
	global_store_dwordx4 v23, v[140:143], s[14:15] offset:2064 nt
	s_add_u32 s14, s14, 0x400000
	s_addc_u32 s15, s15, 0
	s_add_u32 s10, s10, 0x200000
	s_addc_u32 s11, s11, 0
	s_add_u32 s12, s12, 0x10000
	s_addc_u32 s13, s13, 0
	global_load_dword v112, v24, s[12:13]
	global_load_dwordx4 v[80:83], v16, s[10:11]
	global_load_dwordx4 v[84:87], v16, s[10:11] offset:1024
	global_load_dwordx4 v[88:91], v17, s[10:11]
	global_load_dwordx4 v[92:95], v17, s[10:11] offset:1024
	global_load_dwordx4 v[96:99], v18, s[10:11]
	global_load_dwordx4 v[100:103], v18, s[10:11] offset:1024
	global_load_dwordx4 v[104:107], v19, s[10:11]
	global_load_dwordx4 v[108:111], v19, s[10:11] offset:1024
	s_waitcnt vmcnt(33)
	v_add_f32_dpp v26, v72, v72 quad_perm:[1,0,3,2] row_mask:0xf bank_mask:0xf
	s_nop 1
	v_add_f32_dpp v27, v26, v26 quad_perm:[2,3,0,1] row_mask:0xf bank_mask:0xf
	s_nop 1
	v_add_f32_dpp v26, v27, v27 row_half_mirror row_mask:0xf bank_mask:0xf
	s_nop 1
	v_add_f32_dpp v30, v26, v26 row_mirror row_mask:0xf bank_mask:0xf
	v_fmamk_f32 v30, v30, 0x3a800000, v28
	v_mul_f32_e32 v31, 0x4f800000, v30
	v_cmp_gt_f32_e32 vcc, s5, v30
	s_nop 1
	v_cndmask_b32_e32 v30, v30, v31, vcc
	v_sqrt_f32_e32 v31, v30
	s_nop 0
	v_add_u32_e32 v36, -1, v31
	v_add_u32_e32 v37, 1, v31
	v_fma_f32 v38, -v36, v31, v30
	v_fma_f32 v39, -v37, v31, v30
	v_cmp_ge_f32_e64 s[2:3], 0, v38
	s_nop 1
	v_cndmask_b32_e64 v31, v31, v36, s[2:3]
	v_cmp_lt_f32_e64 s[2:3], 0, v39
	s_nop 1
	v_cndmask_b32_e64 v31, v31, v37, s[2:3]
	v_mul_f32_e32 v36, 0x37800000, v31
	v_cndmask_b32_e32 v31, v31, v36, vcc
	v_cmp_class_f32_e32 vcc, v30, v29
	s_nop 1
	v_cndmask_b32_e32 v30, v31, v30, vcc
	v_div_scale_f32 v31, s[2:3], v30, v30, 1.0
	v_rcp_f32_e32 v36, v31
	v_div_scale_f32 v37, vcc, 1.0, v30, 1.0
	v_fma_f32 v38, -v31, v36, 1.0
	v_fmac_f32_e32 v36, v38, v36
	v_mul_f32_e32 v38, v37, v36
	v_fma_f32 v39, -v31, v38, v37
	v_fmac_f32_e32 v38, v39, v36
	v_fma_f32 v31, -v31, v38, v37
	v_div_fmas_f32 v31, v31, v36, v38
	v_div_fixup_f32 v38, v31, v30, 1.0
	s_nop 1
	v_readlane_b32 s20, v38, 0
	v_readlane_b32 s22, v38, 16
	v_readlane_b32 s24, v38, 32
	v_readlane_b32 s26, v38, 48
	s_waitcnt vmcnt(25)
	v_lshlrev_b32_e32 v120, 16, v40
	v_and_b32_e32 v121, 0xffff0000, v40
	v_lshlrev_b32_e32 v122, 16, v41
	v_and_b32_e32 v123, 0xffff0000, v41
	v_lshlrev_b32_e32 v124, 16, v42
	v_and_b32_e32 v125, 0xffff0000, v42
	v_lshlrev_b32_e32 v126, 16, v43
	v_and_b32_e32 v127, 0xffff0000, v43
	v_pk_mul_f32 v[120:121], s[20:21], v[120:121] op_sel_hi:[0,1]
	v_pk_mul_f32 v[122:123], s[20:21], v[122:123] op_sel_hi:[0,1]
	v_pk_mul_f32 v[124:125], s[20:21], v[124:125] op_sel_hi:[0,1]
	v_pk_mul_f32 v[126:127], s[20:21], v[126:127] op_sel_hi:[0,1]
	v_pk_mul_f32 v[120:121], v[4:5], v[120:121]
	v_pk_mul_f32 v[122:123], v[6:7], v[122:123]
	v_pk_mul_f32 v[124:125], v[0:1], v[124:125]
	v_pk_mul_f32 v[126:127], v[2:3], v[126:127]
	global_store_dwordx4 v20, v[120:123], s[14:15] nt
	global_store_dwordx4 v20, v[124:127], s[14:15] offset:16 nt
	v_lshlrev_b32_e32 v136, 16, v44
	v_and_b32_e32 v137, 0xffff0000, v44
	v_lshlrev_b32_e32 v138, 16, v45
	v_and_b32_e32 v139, 0xffff0000, v45
	v_lshlrev_b32_e32 v140, 16, v46
	v_and_b32_e32 v141, 0xffff0000, v46
	v_lshlrev_b32_e32 v142, 16, v47
	v_and_b32_e32 v143, 0xffff0000, v47
	v_pk_mul_f32 v[136:137], s[20:21], v[136:137] op_sel_hi:[0,1]
	v_pk_mul_f32 v[138:139], s[20:21], v[138:139] op_sel_hi:[0,1]
	v_pk_mul_f32 v[140:141], s[20:21], v[140:141] op_sel_hi:[0,1]
	v_pk_mul_f32 v[142:143], s[20:21], v[142:143] op_sel_hi:[0,1]
	v_pk_mul_f32 v[136:137], v[12:13], v[136:137]
	v_pk_mul_f32 v[138:139], v[14:15], v[138:139]
	v_pk_mul_f32 v[140:141], v[8:9], v[140:141]
	v_pk_mul_f32 v[142:143], v[10:11], v[142:143]
	global_store_dwordx4 v20, v[136:139], s[14:15] offset:2048 nt
	global_store_dwordx4 v20, v[140:143], s[14:15] offset:2064 nt
	v_lshlrev_b32_e32 v120, 16, v48
	v_and_b32_e32 v121, 0xffff0000, v48
	v_lshlrev_b32_e32 v122, 16, v49
	v_and_b32_e32 v123, 0xffff0000, v49
	v_lshlrev_b32_e32 v124, 16, v50
	v_and_b32_e32 v125, 0xffff0000, v50
	v_lshlrev_b32_e32 v126, 16, v51
	v_and_b32_e32 v127, 0xffff0000, v51
	v_pk_mul_f32 v[120:121], s[22:23], v[120:121] op_sel_hi:[0,1]
	v_pk_mul_f32 v[122:123], s[22:23], v[122:123] op_sel_hi:[0,1]
	v_pk_mul_f32 v[124:125], s[22:23], v[124:125] op_sel_hi:[0,1]
	v_pk_mul_f32 v[126:127], s[22:23], v[126:127] op_sel_hi:[0,1]
	v_pk_mul_f32 v[120:121], v[4:5], v[120:121]
	v_pk_mul_f32 v[122:123], v[6:7], v[122:123]
	v_pk_mul_f32 v[124:125], v[0:1], v[124:125]
	v_pk_mul_f32 v[126:127], v[2:3], v[126:127]
	global_store_dwordx4 v21, v[120:123], s[14:15] nt
	global_store_dwordx4 v21, v[124:127], s[14:15] offset:16 nt
	v_lshlrev_b32_e32 v136, 16, v52
	v_and_b32_e32 v137, 0xffff0000, v52
	v_lshlrev_b32_e32 v138, 16, v53
	v_and_b32_e32 v139, 0xffff0000, v53
	v_lshlrev_b32_e32 v140, 16, v54
	v_and_b32_e32 v141, 0xffff0000, v54
	v_lshlrev_b32_e32 v142, 16, v55
	v_and_b32_e32 v143, 0xffff0000, v55
	v_pk_mul_f32 v[136:137], s[22:23], v[136:137] op_sel_hi:[0,1]
	v_pk_mul_f32 v[138:139], s[22:23], v[138:139] op_sel_hi:[0,1]
	v_pk_mul_f32 v[140:141], s[22:23], v[140:141] op_sel_hi:[0,1]
	v_pk_mul_f32 v[142:143], s[22:23], v[142:143] op_sel_hi:[0,1]
	v_pk_mul_f32 v[136:137], v[12:13], v[136:137]
	v_pk_mul_f32 v[138:139], v[14:15], v[138:139]
	v_pk_mul_f32 v[140:141], v[8:9], v[140:141]
	v_pk_mul_f32 v[142:143], v[10:11], v[142:143]
	global_store_dwordx4 v21, v[136:139], s[14:15] offset:2048 nt
	global_store_dwordx4 v21, v[140:143], s[14:15] offset:2064 nt
	v_lshlrev_b32_e32 v120, 16, v56
	v_and_b32_e32 v121, 0xffff0000, v56
	v_lshlrev_b32_e32 v122, 16, v57
	v_and_b32_e32 v123, 0xffff0000, v57
	v_lshlrev_b32_e32 v124, 16, v58
	v_and_b32_e32 v125, 0xffff0000, v58
	v_lshlrev_b32_e32 v126, 16, v59
	v_and_b32_e32 v127, 0xffff0000, v59
	v_pk_mul_f32 v[120:121], s[24:25], v[120:121] op_sel_hi:[0,1]
	v_pk_mul_f32 v[122:123], s[24:25], v[122:123] op_sel_hi:[0,1]
	v_pk_mul_f32 v[124:125], s[24:25], v[124:125] op_sel_hi:[0,1]
	v_pk_mul_f32 v[126:127], s[24:25], v[126:127] op_sel_hi:[0,1]
	v_pk_mul_f32 v[120:121], v[4:5], v[120:121]
	v_pk_mul_f32 v[122:123], v[6:7], v[122:123]
	v_pk_mul_f32 v[124:125], v[0:1], v[124:125]
	v_pk_mul_f32 v[126:127], v[2:3], v[126:127]
	global_store_dwordx4 v22, v[120:123], s[14:15] nt
	global_store_dwordx4 v22, v[124:127], s[14:15] offset:16 nt
	v_lshlrev_b32_e32 v136, 16, v60
	v_and_b32_e32 v137, 0xffff0000, v60
	v_lshlrev_b32_e32 v138, 16, v61
	v_and_b32_e32 v139, 0xffff0000, v61
	v_lshlrev_b32_e32 v140, 16, v62
	v_and_b32_e32 v141, 0xffff0000, v62
	v_lshlrev_b32_e32 v142, 16, v63
	v_and_b32_e32 v143, 0xffff0000, v63
	v_pk_mul_f32 v[136:137], s[24:25], v[136:137] op_sel_hi:[0,1]
	v_pk_mul_f32 v[138:139], s[24:25], v[138:139] op_sel_hi:[0,1]
	v_pk_mul_f32 v[140:141], s[24:25], v[140:141] op_sel_hi:[0,1]
	v_pk_mul_f32 v[142:143], s[24:25], v[142:143] op_sel_hi:[0,1]
	v_pk_mul_f32 v[136:137], v[12:13], v[136:137]
	v_pk_mul_f32 v[138:139], v[14:15], v[138:139]
	v_pk_mul_f32 v[140:141], v[8:9], v[140:141]
	v_pk_mul_f32 v[142:143], v[10:11], v[142:143]
	global_store_dwordx4 v22, v[136:139], s[14:15] offset:2048 nt
	global_store_dwordx4 v22, v[140:143], s[14:15] offset:2064 nt
	v_lshlrev_b32_e32 v120, 16, v64
	v_and_b32_e32 v121, 0xffff0000, v64
	v_lshlrev_b32_e32 v122, 16, v65
	v_and_b32_e32 v123, 0xffff0000, v65
	v_lshlrev_b32_e32 v124, 16, v66
	v_and_b32_e32 v125, 0xffff0000, v66
	v_lshlrev_b32_e32 v126, 16, v67
	v_and_b32_e32 v127, 0xffff0000, v67
	v_pk_mul_f32 v[120:121], s[26:27], v[120:121] op_sel_hi:[0,1]
	v_pk_mul_f32 v[122:123], s[26:27], v[122:123] op_sel_hi:[0,1]
	v_pk_mul_f32 v[124:125], s[26:27], v[124:125] op_sel_hi:[0,1]
	v_pk_mul_f32 v[126:127], s[26:27], v[126:127] op_sel_hi:[0,1]
	v_pk_mul_f32 v[120:121], v[4:5], v[120:121]
	v_pk_mul_f32 v[122:123], v[6:7], v[122:123]
	v_pk_mul_f32 v[124:125], v[0:1], v[124:125]
	v_pk_mul_f32 v[126:127], v[2:3], v[126:127]
	global_store_dwordx4 v23, v[120:123], s[14:15] nt
	global_store_dwordx4 v23, v[124:127], s[14:15] offset:16 nt
	v_lshlrev_b32_e32 v136, 16, v68
	v_and_b32_e32 v137, 0xffff0000, v68
	v_lshlrev_b32_e32 v138, 16, v69
	v_and_b32_e32 v139, 0xffff0000, v69
	v_lshlrev_b32_e32 v140, 16, v70
	v_and_b32_e32 v141, 0xffff0000, v70
	v_lshlrev_b32_e32 v142, 16, v71
	v_and_b32_e32 v143, 0xffff0000, v71
	v_pk_mul_f32 v[136:137], s[26:27], v[136:137] op_sel_hi:[0,1]
	v_pk_mul_f32 v[138:139], s[26:27], v[138:139] op_sel_hi:[0,1]
	v_pk_mul_f32 v[140:141], s[26:27], v[140:141] op_sel_hi:[0,1]
	v_pk_mul_f32 v[142:143], s[26:27], v[142:143] op_sel_hi:[0,1]
	v_pk_mul_f32 v[136:137], v[12:13], v[136:137]
	v_pk_mul_f32 v[138:139], v[14:15], v[138:139]
	v_pk_mul_f32 v[140:141], v[8:9], v[140:141]
	v_pk_mul_f32 v[142:143], v[10:11], v[142:143]
	global_store_dwordx4 v23, v[136:139], s[14:15] offset:2048 nt
	global_store_dwordx4 v23, v[140:143], s[14:15] offset:2064 nt
	s_add_u32 s14, s14, 0x400000
	s_addc_u32 s15, s15, 0
	s_waitcnt vmcnt(24)
	v_add_f32_dpp v26, v112, v112 quad_perm:[1,0,3,2] row_mask:0xf bank_mask:0xf
	s_nop 1
	v_add_f32_dpp v27, v26, v26 quad_perm:[2,3,0,1] row_mask:0xf bank_mask:0xf
	s_nop 1
	v_add_f32_dpp v26, v27, v27 row_half_mirror row_mask:0xf bank_mask:0xf
	s_nop 1
	v_add_f32_dpp v30, v26, v26 row_mirror row_mask:0xf bank_mask:0xf
	v_fmamk_f32 v30, v30, 0x3a800000, v28
	v_mul_f32_e32 v31, 0x4f800000, v30
	v_cmp_gt_f32_e32 vcc, s5, v30
	s_nop 1
	v_cndmask_b32_e32 v30, v30, v31, vcc
	v_sqrt_f32_e32 v31, v30
	s_nop 0
	v_add_u32_e32 v36, -1, v31
	v_add_u32_e32 v37, 1, v31
	v_fma_f32 v38, -v36, v31, v30
	v_fma_f32 v39, -v37, v31, v30
	v_cmp_ge_f32_e64 s[2:3], 0, v38
	s_nop 1
	v_cndmask_b32_e64 v31, v31, v36, s[2:3]
	v_cmp_lt_f32_e64 s[2:3], 0, v39
	s_nop 1
	v_cndmask_b32_e64 v31, v31, v37, s[2:3]
	v_mul_f32_e32 v36, 0x37800000, v31
	v_cndmask_b32_e32 v31, v31, v36, vcc
	v_cmp_class_f32_e32 vcc, v30, v29
	s_nop 1
	v_cndmask_b32_e32 v30, v31, v30, vcc
	v_div_scale_f32 v31, s[2:3], v30, v30, 1.0
	v_rcp_f32_e32 v36, v31
	v_div_scale_f32 v37, vcc, 1.0, v30, 1.0
	v_fma_f32 v38, -v31, v36, 1.0
	v_fmac_f32_e32 v36, v38, v36
	v_mul_f32_e32 v38, v37, v36
	v_fma_f32 v39, -v31, v38, v37
	v_fmac_f32_e32 v38, v39, v36
	v_fma_f32 v31, -v31, v38, v37
	v_div_fmas_f32 v31, v31, v36, v38
	v_div_fixup_f32 v38, v31, v30, 1.0
	s_nop 1
	v_readlane_b32 s20, v38, 0
	v_readlane_b32 s22, v38, 16
	v_readlane_b32 s24, v38, 32
	v_readlane_b32 s26, v38, 48
	s_waitcnt vmcnt(16)
	v_lshlrev_b32_e32 v120, 16, v80
	v_and_b32_e32 v121, 0xffff0000, v80
	v_lshlrev_b32_e32 v122, 16, v81
	v_and_b32_e32 v123, 0xffff0000, v81
	v_lshlrev_b32_e32 v124, 16, v82
	v_and_b32_e32 v125, 0xffff0000, v82
	v_lshlrev_b32_e32 v126, 16, v83
	v_and_b32_e32 v127, 0xffff0000, v83
	v_pk_mul_f32 v[120:121], s[20:21], v[120:121] op_sel_hi:[0,1]
	v_pk_mul_f32 v[122:123], s[20:21], v[122:123] op_sel_hi:[0,1]
	v_pk_mul_f32 v[124:125], s[20:21], v[124:125] op_sel_hi:[0,1]
	v_pk_mul_f32 v[126:127], s[20:21], v[126:127] op_sel_hi:[0,1]
	v_pk_mul_f32 v[120:121], v[4:5], v[120:121]
	v_pk_mul_f32 v[122:123], v[6:7], v[122:123]
	v_pk_mul_f32 v[124:125], v[0:1], v[124:125]
	v_pk_mul_f32 v[126:127], v[2:3], v[126:127]
	global_store_dwordx4 v20, v[120:123], s[14:15] nt
	global_store_dwordx4 v20, v[124:127], s[14:15] offset:16 nt
	v_lshlrev_b32_e32 v136, 16, v84
	v_and_b32_e32 v137, 0xffff0000, v84
	v_lshlrev_b32_e32 v138, 16, v85
	v_and_b32_e32 v139, 0xffff0000, v85
	v_lshlrev_b32_e32 v140, 16, v86
	v_and_b32_e32 v141, 0xffff0000, v86
	v_lshlrev_b32_e32 v142, 16, v87
	v_and_b32_e32 v143, 0xffff0000, v87
	v_pk_mul_f32 v[136:137], s[20:21], v[136:137] op_sel_hi:[0,1]
	v_pk_mul_f32 v[138:139], s[20:21], v[138:139] op_sel_hi:[0,1]
	v_pk_mul_f32 v[140:141], s[20:21], v[140:141] op_sel_hi:[0,1]
	v_pk_mul_f32 v[142:143], s[20:21], v[142:143] op_sel_hi:[0,1]
	v_pk_mul_f32 v[136:137], v[12:13], v[136:137]
	v_pk_mul_f32 v[138:139], v[14:15], v[138:139]
	v_pk_mul_f32 v[140:141], v[8:9], v[140:141]
	v_pk_mul_f32 v[142:143], v[10:11], v[142:143]
	global_store_dwordx4 v20, v[136:139], s[14:15] offset:2048 nt
	global_store_dwordx4 v20, v[140:143], s[14:15] offset:2064 nt
	v_lshlrev_b32_e32 v120, 16, v88
	v_and_b32_e32 v121, 0xffff0000, v88
	v_lshlrev_b32_e32 v122, 16, v89
	v_and_b32_e32 v123, 0xffff0000, v89
	v_lshlrev_b32_e32 v124, 16, v90
	v_and_b32_e32 v125, 0xffff0000, v90
	v_lshlrev_b32_e32 v126, 16, v91
	v_and_b32_e32 v127, 0xffff0000, v91
	v_pk_mul_f32 v[120:121], s[22:23], v[120:121] op_sel_hi:[0,1]
	v_pk_mul_f32 v[122:123], s[22:23], v[122:123] op_sel_hi:[0,1]
	v_pk_mul_f32 v[124:125], s[22:23], v[124:125] op_sel_hi:[0,1]
	v_pk_mul_f32 v[126:127], s[22:23], v[126:127] op_sel_hi:[0,1]
	v_pk_mul_f32 v[120:121], v[4:5], v[120:121]
	v_pk_mul_f32 v[122:123], v[6:7], v[122:123]
	v_pk_mul_f32 v[124:125], v[0:1], v[124:125]
	v_pk_mul_f32 v[126:127], v[2:3], v[126:127]
	global_store_dwordx4 v21, v[120:123], s[14:15] nt
	global_store_dwordx4 v21, v[124:127], s[14:15] offset:16 nt
	v_lshlrev_b32_e32 v136, 16, v92
	v_and_b32_e32 v137, 0xffff0000, v92
	v_lshlrev_b32_e32 v138, 16, v93
	v_and_b32_e32 v139, 0xffff0000, v93
	v_lshlrev_b32_e32 v140, 16, v94
	v_and_b32_e32 v141, 0xffff0000, v94
	v_lshlrev_b32_e32 v142, 16, v95
	v_and_b32_e32 v143, 0xffff0000, v95
	v_pk_mul_f32 v[136:137], s[22:23], v[136:137] op_sel_hi:[0,1]
	v_pk_mul_f32 v[138:139], s[22:23], v[138:139] op_sel_hi:[0,1]
	v_pk_mul_f32 v[140:141], s[22:23], v[140:141] op_sel_hi:[0,1]
	v_pk_mul_f32 v[142:143], s[22:23], v[142:143] op_sel_hi:[0,1]
	v_pk_mul_f32 v[136:137], v[12:13], v[136:137]
	v_pk_mul_f32 v[138:139], v[14:15], v[138:139]
	v_pk_mul_f32 v[140:141], v[8:9], v[140:141]
	v_pk_mul_f32 v[142:143], v[10:11], v[142:143]
	global_store_dwordx4 v21, v[136:139], s[14:15] offset:2048 nt
	global_store_dwordx4 v21, v[140:143], s[14:15] offset:2064 nt
	v_lshlrev_b32_e32 v120, 16, v96
	v_and_b32_e32 v121, 0xffff0000, v96
	v_lshlrev_b32_e32 v122, 16, v97
	v_and_b32_e32 v123, 0xffff0000, v97
	v_lshlrev_b32_e32 v124, 16, v98
	v_and_b32_e32 v125, 0xffff0000, v98
	v_lshlrev_b32_e32 v126, 16, v99
	v_and_b32_e32 v127, 0xffff0000, v99
	v_pk_mul_f32 v[120:121], s[24:25], v[120:121] op_sel_hi:[0,1]
	v_pk_mul_f32 v[122:123], s[24:25], v[122:123] op_sel_hi:[0,1]
	v_pk_mul_f32 v[124:125], s[24:25], v[124:125] op_sel_hi:[0,1]
	v_pk_mul_f32 v[126:127], s[24:25], v[126:127] op_sel_hi:[0,1]
	v_pk_mul_f32 v[120:121], v[4:5], v[120:121]
	v_pk_mul_f32 v[122:123], v[6:7], v[122:123]
	v_pk_mul_f32 v[124:125], v[0:1], v[124:125]
	v_pk_mul_f32 v[126:127], v[2:3], v[126:127]
	global_store_dwordx4 v22, v[120:123], s[14:15] nt
	global_store_dwordx4 v22, v[124:127], s[14:15] offset:16 nt
	v_lshlrev_b32_e32 v136, 16, v100
	v_and_b32_e32 v137, 0xffff0000, v100
	v_lshlrev_b32_e32 v138, 16, v101
	v_and_b32_e32 v139, 0xffff0000, v101
	v_lshlrev_b32_e32 v140, 16, v102
	v_and_b32_e32 v141, 0xffff0000, v102
	v_lshlrev_b32_e32 v142, 16, v103
	v_and_b32_e32 v143, 0xffff0000, v103
	v_pk_mul_f32 v[136:137], s[24:25], v[136:137] op_sel_hi:[0,1]
	v_pk_mul_f32 v[138:139], s[24:25], v[138:139] op_sel_hi:[0,1]
	v_pk_mul_f32 v[140:141], s[24:25], v[140:141] op_sel_hi:[0,1]
	v_pk_mul_f32 v[142:143], s[24:25], v[142:143] op_sel_hi:[0,1]
	v_pk_mul_f32 v[136:137], v[12:13], v[136:137]
	v_pk_mul_f32 v[138:139], v[14:15], v[138:139]
	v_pk_mul_f32 v[140:141], v[8:9], v[140:141]
	v_pk_mul_f32 v[142:143], v[10:11], v[142:143]
	global_store_dwordx4 v22, v[136:139], s[14:15] offset:2048 nt
	global_store_dwordx4 v22, v[140:143], s[14:15] offset:2064 nt
	v_lshlrev_b32_e32 v120, 16, v104
	v_and_b32_e32 v121, 0xffff0000, v104
	v_lshlrev_b32_e32 v122, 16, v105
	v_and_b32_e32 v123, 0xffff0000, v105
	v_lshlrev_b32_e32 v124, 16, v106
	v_and_b32_e32 v125, 0xffff0000, v106
	v_lshlrev_b32_e32 v126, 16, v107
	v_and_b32_e32 v127, 0xffff0000, v107
	v_pk_mul_f32 v[120:121], s[26:27], v[120:121] op_sel_hi:[0,1]
	v_pk_mul_f32 v[122:123], s[26:27], v[122:123] op_sel_hi:[0,1]
	v_pk_mul_f32 v[124:125], s[26:27], v[124:125] op_sel_hi:[0,1]
	v_pk_mul_f32 v[126:127], s[26:27], v[126:127] op_sel_hi:[0,1]
	v_pk_mul_f32 v[120:121], v[4:5], v[120:121]
	v_pk_mul_f32 v[122:123], v[6:7], v[122:123]
	v_pk_mul_f32 v[124:125], v[0:1], v[124:125]
	v_pk_mul_f32 v[126:127], v[2:3], v[126:127]
	global_store_dwordx4 v23, v[120:123], s[14:15] nt
	global_store_dwordx4 v23, v[124:127], s[14:15] offset:16 nt
	v_lshlrev_b32_e32 v136, 16, v108
	v_and_b32_e32 v137, 0xffff0000, v108
	v_lshlrev_b32_e32 v138, 16, v109
	v_and_b32_e32 v139, 0xffff0000, v109
	v_lshlrev_b32_e32 v140, 16, v110
	v_and_b32_e32 v141, 0xffff0000, v110
	v_lshlrev_b32_e32 v142, 16, v111
	v_and_b32_e32 v143, 0xffff0000, v111
	v_pk_mul_f32 v[136:137], s[26:27], v[136:137] op_sel_hi:[0,1]
	v_pk_mul_f32 v[138:139], s[26:27], v[138:139] op_sel_hi:[0,1]
	v_pk_mul_f32 v[140:141], s[26:27], v[140:141] op_sel_hi:[0,1]
	v_pk_mul_f32 v[142:143], s[26:27], v[142:143] op_sel_hi:[0,1]
	v_pk_mul_f32 v[136:137], v[12:13], v[136:137]
	v_pk_mul_f32 v[138:139], v[14:15], v[138:139]
	v_pk_mul_f32 v[140:141], v[8:9], v[140:141]
	v_pk_mul_f32 v[142:143], v[10:11], v[142:143]
	global_store_dwordx4 v23, v[136:139], s[14:15] offset:2048 nt
	global_store_dwordx4 v23, v[140:143], s[14:15] offset:2064 nt
	s_add_u32 s14, s14, 0x400000
	s_addc_u32 s15, s15, 0
